# GEMM main loops: per-phase s_setprio toggles removed (all five GEMM phases)
# speedup vs baseline: 1.0096x; 1.0082x over previous
; #define PG8_STAGE(bufoff, gbase, voff) do { _Pragma("unroll") for (int _i = 0; _i < 2; ++_i) \
;         __builtin_amdgcn_global_load_lds((const unsigned*)((const char*)(gbase) + (voff)[_i]), (PG8_LAS unsigned*)(lds + (bufoff) + ldsw + _i * 8192), 16, 0, 0); } while (0)
; #define PG8_LDA(dst, b, h) do { int aoff; asm volatile("v_add_u32 %0, %1, %2" : "=v"(aoff) : "s"(ua), "v"(foff)); _Pragma("unroll") for (int m = 0; m < 4; ++m) _Pragma("unroll") for (int k = 0; k < 2; ++k) dst[m][k] = *(const PG8_LAS bf16x8*)(lds + PG8_SA(b, h) + aoff + m * 2048 + k * 1024); } while (0)
; #define PG8_LDB(dst, b, h) do { int boff; asm volatile("v_add_u32 %0, %1, %2" : "=v"(boff) : "s"(ub), "v"(foff)); _Pragma("unroll") for (int n = 0; n < 2; ++n) _Pragma("unroll") for (int k = 0; k < 2; ++k) dst[n][k] = *(const PG8_LAS bf16x8*)(lds + PG8_SB(b, h) + boff + n * 2048 + k * 1024); } while (0)
; #define PG8_MMA(ai, bj, At, Bt) do { __builtin_amdgcn_s_setprio(1); _Pragma("unroll") for (int m = 0; m < 4; ++m) _Pragma("unroll") for (int n = 0; n < 2; ++n) _Pragma("unroll") for (int k = 0; k < 2; ++k) \
;         acc[ai][bj][m][n] = __builtin_amdgcn_mfma_f32_16x16x32_bf16(Bt[n][k], At[m][k], acc[ai][bj][m][n], 0, 0, 0); __builtin_amdgcn_s_setprio(0); } while (0)
; #define PG8_WAIT_L(n) asm volatile("s_waitcnt lgkmcnt(" #n ")" ::: "memory")
; #define PG8_BAR __builtin_amdgcn_s_barrier()
; #define PG8_SCHED __builtin_amdgcn_sched_barrier(0)
; template <class Epi, class Sched>
; __device__ __forceinline__ void gemm_phase(PG8_LAS unsigned char* lds, const Gemm g, const Sched& S, const Epi& E) {
;     ...
;             PG8_LDB(B0, 0, 0); PG8_SCHED; PG8_LDA(At, 0, 0); PG8_STAGE(PG8_SA(1, 1), a1 + hstep, voffA);
;             PG8_WAIT_L(8); PG8_BAR; PG8_WAIT_L(0); PG8_MMA(0, 0, At, B0); PG8_BAR; PG8_SCHED;
;             PG8_LDB(B1, 0, 1); PG8_STAGE(PG8_SB(0, 0), b2, voffB);
;             PG8_BAR; PG8_WAIT_L(0); PG8_MMA(0, 1, At, B1); PG8_BAR;
;             PG8_LDA(At, 0, 1); PG8_STAGE(PG8_SA(0, 0), a2, voffA);
;             PG8_BAR; PG8_WAIT_L(0); PG8_MMA(1, 0, At, B0); PG8_BAR; PG8_SCHED;
.LBB0_478:
	s_add_u32 s18, s28, 0xfffc0080
	s_addc_u32 s19, s29, -1
	s_add_i32 s60, 0, 0x10000
	v_add_u32 v144, s45, v1
	s_cmp_eq_u32 s54, 12
	v_add_u32_e32 v144, s60, v144
	ds_read_b128 v[156:159], v144
	ds_read_b128 v[160:163], v144 offset:1024
	ds_read_b128 v[164:167], v144 offset:2048
	ds_read_b128 v[168:171], v144 offset:3072
	s_cselect_b32 s43, s21, s19
	s_cselect_b32 s42, s50, s18
	s_cselect_b32 s41, s17, s53
	s_cselect_b32 s40, s51, s52
	v_add_u32 v144, s44, v1
	s_add_i32 m0, s3, 0xc000
	v_add_u32_e32 v144, 0, v144
	ds_read_b128 v[172:175], v144
	ds_read_b128 v[176:179], v144 offset:1024
	ds_read_b128 v[180:183], v144 offset:2048
	ds_read_b128 v[184:187], v144 offset:3072
	ds_read_b128 v[188:191], v144 offset:4096
	ds_read_b128 v[192:195], v144 offset:5120
	ds_read_b128 v[196:199], v144 offset:6144
	ds_read_b128 v[200:203], v144 offset:7168
	v_lshl_add_u64 v[144:145], s[28:29], 0, v[138:139]
	global_load_lds_dwordx4 v[144:145], off
	v_lshl_add_u64 v[144:145], s[28:29], 0, v[140:141]
	s_add_i32 m0, s3, 0xe000
	s_nop 0
	global_load_lds_dwordx4 v[144:145], off
	s_waitcnt lgkmcnt(8)
	s_barrier
	s_waitcnt lgkmcnt(0)
	s_waitcnt lgkmcnt(0)
	v_mfma_f32_16x16x32_bf16 v[126:129], v[156:159], v[172:175], v[126:129]
	v_mfma_f32_16x16x32_bf16 v[122:125], v[164:167], v[172:175], v[122:125]
	v_mfma_f32_16x16x32_bf16 v[118:121], v[156:159], v[180:183], v[118:121]
	v_mfma_f32_16x16x32_bf16 v[114:117], v[164:167], v[180:183], v[114:117]
	v_mfma_f32_16x16x32_bf16 v[102:105], v[156:159], v[188:191], v[102:105]
	v_mfma_f32_16x16x32_bf16 v[98:101], v[164:167], v[188:191], v[98:101]
	v_mfma_f32_16x16x32_bf16 v[86:89], v[156:159], v[196:199], v[86:89]
	v_mfma_f32_16x16x32_bf16 v[82:85], v[164:167], v[196:199], v[82:85]
	v_mfma_f32_16x16x32_bf16 v[126:129], v[160:163], v[176:179], v[126:129]
	v_mfma_f32_16x16x32_bf16 v[122:125], v[168:171], v[176:179], v[122:125]
	v_mfma_f32_16x16x32_bf16 v[118:121], v[160:163], v[184:187], v[118:121]
	v_mfma_f32_16x16x32_bf16 v[114:117], v[168:171], v[184:187], v[114:117]
	v_mfma_f32_16x16x32_bf16 v[102:105], v[160:163], v[192:195], v[102:105]
	v_mfma_f32_16x16x32_bf16 v[98:101], v[168:171], v[192:195], v[98:101]
	v_mfma_f32_16x16x32_bf16 v[86:89], v[160:163], v[200:203], v[86:89]
	v_mfma_f32_16x16x32_bf16 v[82:85], v[168:171], v[200:203], v[82:85]
	s_barrier
	v_add_u32 v144, s45, v1
	s_add_i32 s18, 0, 0x14000
	v_add_u32_e32 v144, s18, v144
	s_add_i32 s19, s60, s10
	ds_read_b128 v[224:227], v144
	ds_read_b128 v[228:231], v144 offset:1024
	ds_read_b128 v[232:235], v144 offset:2048
	ds_read_b128 v[236:239], v144 offset:3072
	v_lshl_add_u64 v[144:145], s[40:41], 0, v[134:135]
	s_mov_b32 m0, s19
	v_lshl_add_u64 v[146:147], s[40:41], 0, v[130:131]
	global_load_lds_dwordx4 v[144:145], off
	s_add_i32 m0, s19, 0x2000
	s_nop 0
	global_load_lds_dwordx4 v[146:147], off
	s_barrier
	s_waitcnt lgkmcnt(0)
	s_waitcnt lgkmcnt(0)
	v_mfma_f32_16x16x32_bf16 v[110:113], v[224:227], v[172:175], v[110:113]
	v_mfma_f32_16x16x32_bf16 v[106:109], v[232:235], v[172:175], v[106:109]
	v_mfma_f32_16x16x32_bf16 v[94:97], v[224:227], v[180:183], v[94:97]
	v_mfma_f32_16x16x32_bf16 v[90:93], v[232:235], v[180:183], v[90:93]
	v_mfma_f32_16x16x32_bf16 v[78:81], v[224:227], v[188:191], v[78:81]
	v_mfma_f32_16x16x32_bf16 v[74:77], v[232:235], v[188:191], v[74:77]
	v_mfma_f32_16x16x32_bf16 v[70:73], v[224:227], v[196:199], v[70:73]
	v_mfma_f32_16x16x32_bf16 v[66:69], v[232:235], v[196:199], v[66:69]
	v_mfma_f32_16x16x32_bf16 v[110:113], v[228:231], v[176:179], v[110:113]
	v_mfma_f32_16x16x32_bf16 v[106:109], v[236:239], v[176:179], v[106:109]
	v_mfma_f32_16x16x32_bf16 v[94:97], v[228:231], v[184:187], v[94:97]
	v_mfma_f32_16x16x32_bf16 v[90:93], v[236:239], v[184:187], v[90:93]
	v_mfma_f32_16x16x32_bf16 v[78:81], v[228:231], v[192:195], v[78:81]
	v_mfma_f32_16x16x32_bf16 v[74:77], v[236:239], v[192:195], v[74:77]
	v_mfma_f32_16x16x32_bf16 v[70:73], v[228:231], v[200:203], v[70:73]
	v_mfma_f32_16x16x32_bf16 v[66:69], v[236:239], v[200:203], v[66:69]
	s_barrier
	v_add_u32 v148, s44, v1
	s_mov_b32 m0, s3
	v_add_u32_e32 v148, 0, v148
	ds_read_b128 v[172:175], v148 offset:16384
	ds_read_b128 v[176:179], v148 offset:17408
	ds_read_b128 v[180:183], v148 offset:18432
	ds_read_b128 v[184:187], v148 offset:19456
	ds_read_b128 v[188:191], v148 offset:20480
	ds_read_b128 v[192:195], v148 offset:21504
	ds_read_b128 v[196:199], v148 offset:22528
	ds_read_b128 v[200:203], v148 offset:23552
	v_lshl_add_u64 v[148:149], s[42:43], 0, v[136:137]
	global_load_lds_dwordx4 v[148:149], off
	v_lshl_add_u64 v[150:151], s[42:43], 0, v[132:133]
	s_mov_b32 m0, s5
	s_nop 0
	global_load_lds_dwordx4 v[150:151], off
	s_barrier
	s_waitcnt lgkmcnt(0)
	s_waitcnt lgkmcnt(0)
	v_mfma_f32_16x16x32_bf16 v[62:65], v[156:159], v[172:175], v[62:65]
	v_mfma_f32_16x16x32_bf16 v[58:61], v[164:167], v[172:175], v[58:61]
	v_mfma_f32_16x16x32_bf16 v[54:57], v[156:159], v[180:183], v[54:57]
	v_mfma_f32_16x16x32_bf16 v[50:53], v[164:167], v[180:183], v[50:53]
	v_mfma_f32_16x16x32_bf16 v[38:41], v[156:159], v[188:191], v[38:41]
	v_mfma_f32_16x16x32_bf16 v[34:37], v[164:167], v[188:191], v[34:37]
	v_mfma_f32_16x16x32_bf16 v[22:25], v[156:159], v[196:199], v[22:25]
	v_mfma_f32_16x16x32_bf16 v[18:21], v[164:167], v[196:199], v[18:21]
	v_mfma_f32_16x16x32_bf16 v[62:65], v[160:163], v[176:179], v[62:65]
	v_mfma_f32_16x16x32_bf16 v[58:61], v[168:171], v[176:179], v[58:61]
	v_mfma_f32_16x16x32_bf16 v[54:57], v[160:163], v[184:187], v[54:57]
	v_mfma_f32_16x16x32_bf16 v[50:53], v[168:171], v[184:187], v[50:53]
	v_mfma_f32_16x16x32_bf16 v[38:41], v[160:163], v[192:195], v[38:41]
	v_mfma_f32_16x16x32_bf16 v[34:37], v[168:171], v[192:195], v[34:37]
	v_mfma_f32_16x16x32_bf16 v[22:25], v[160:163], v[200:203], v[22:25]
	v_mfma_f32_16x16x32_bf16 v[18:21], v[168:171], v[200:203], v[18:21]
	s_barrier
; #define PG8_STAGE(bufoff, gbase, voff) do { _Pragma("unroll") for (int _i = 0; _i < 2; ++_i) \
;         __builtin_amdgcn_global_load_lds((const unsigned*)((const char*)(gbase) + (voff)[_i]), (PG8_LAS unsigned*)(lds + (bufoff) + ldsw + _i * 8192), 16, 0, 0); } while (0)
; #define PG8_LDA(dst, b, h) do { int aoff; asm volatile("v_add_u32 %0, %1, %2" : "=v"(aoff) : "s"(ua), "v"(foff)); _Pragma("unroll") for (int m = 0; m < 4; ++m) _Pragma("unroll") for (int k = 0; k < 2; ++k) dst[m][k] = *(const PG8_LAS bf16x8*)(lds + PG8_SA(b, h) + aoff + m * 2048 + k * 1024); } while (0)
; #define PG8_LDB(dst, b, h) do { int boff; asm volatile("v_add_u32 %0, %1, %2" : "=v"(boff) : "s"(ub), "v"(foff)); _Pragma("unroll") for (int n = 0; n < 2; ++n) _Pragma("unroll") for (int k = 0; k < 2; ++k) dst[n][k] = *(const PG8_LAS bf16x8*)(lds + PG8_SB(b, h) + boff + n * 2048 + k * 1024); } while (0)
; #define PG8_MMA(ai, bj, At, Bt) do { __builtin_amdgcn_s_setprio(1); _Pragma("unroll") for (int m = 0; m < 4; ++m) _Pragma("unroll") for (int n = 0; n < 2; ++n) _Pragma("unroll") for (int k = 0; k < 2; ++k) \
;         acc[ai][bj][m][n] = __builtin_amdgcn_mfma_f32_16x16x32_bf16(Bt[n][k], At[m][k], acc[ai][bj][m][n], 0, 0, 0); __builtin_amdgcn_s_setprio(0); } while (0)
; #define PG8_WAIT_V(n) asm volatile("s_waitcnt vmcnt(" #n ")" ::: "memory")
; #define PG8_WAIT_L(n) asm volatile("s_waitcnt lgkmcnt(" #n ")" ::: "memory")
; #define PG8_BAR __builtin_amdgcn_s_barrier()
; #define PG8_SCHED __builtin_amdgcn_sched_barrier(0)
; template <class Epi, class Sched>
; __device__ __forceinline__ void gemm_phase(PG8_LAS unsigned char* lds, const Gemm g, const Sched& S, const Epi& E) {
;     ...
;             PG8_STAGE(PG8_SB(0, 1), b2 + hstep, voffB);
;             PG8_WAIT_V(6); PG8_BAR; PG8_MMA(1, 1, At, B1); PG8_BAR;
;             PG8_LDB(B0, 1, 0); PG8_SCHED; PG8_LDA(At, 1, 0); PG8_STAGE(PG8_SA(0, 1), a2 + hstep, voffA);
;             PG8_WAIT_L(8); PG8_BAR; PG8_WAIT_L(0); PG8_MMA(0, 0, At, B0); PG8_BAR; PG8_SCHED;
;             PG8_LDB(B1, 1, 1); PG8_STAGE(PG8_SB(1, 0), b3, voffB);
;             PG8_BAR; PG8_WAIT_L(0); PG8_MMA(0, 1, At, B1); PG8_BAR;
	s_add_u32 s60, s40, 0x40000
	s_addc_u32 s61, s41, 0
	s_add_i32 s18, s18, s10
	v_lshl_add_u64 v[152:153], s[60:61], 0, v[134:135]
	s_mov_b32 m0, s18
	s_nop 0
	global_load_lds_dwordx4 v[152:153], off
	v_lshl_add_u64 v[152:153], s[60:61], 0, v[130:131]
	s_add_i32 m0, s18, 0x2000
	s_nop 0
	global_load_lds_dwordx4 v[152:153], off
	s_waitcnt vmcnt(6)
	s_barrier
	v_mfma_f32_16x16x32_bf16 v[46:49], v[224:227], v[172:175], v[46:49]
	v_mfma_f32_16x16x32_bf16 v[42:45], v[232:235], v[172:175], v[42:45]
	v_mfma_f32_16x16x32_bf16 v[30:33], v[224:227], v[180:183], v[30:33]
	v_mfma_f32_16x16x32_bf16 v[26:29], v[232:235], v[180:183], v[26:29]
	v_mfma_f32_16x16x32_bf16 v[14:17], v[224:227], v[188:191], v[14:17]
	v_mfma_f32_16x16x32_bf16 v[10:13], v[232:235], v[188:191], v[10:13]
	v_mfma_f32_16x16x32_bf16 v[6:9], v[224:227], v[196:199], v[6:9]
	v_mfma_f32_16x16x32_bf16 v[2:5], v[232:235], v[196:199], v[2:5]
	v_mfma_f32_16x16x32_bf16 v[46:49], v[228:231], v[176:179], v[46:49]
	v_mfma_f32_16x16x32_bf16 v[42:45], v[236:239], v[176:179], v[42:45]
	v_mfma_f32_16x16x32_bf16 v[30:33], v[228:231], v[184:187], v[30:33]
	v_mfma_f32_16x16x32_bf16 v[26:29], v[236:239], v[184:187], v[26:29]
	v_mfma_f32_16x16x32_bf16 v[14:17], v[228:231], v[192:195], v[14:17]
	v_mfma_f32_16x16x32_bf16 v[10:13], v[236:239], v[192:195], v[10:13]
	v_mfma_f32_16x16x32_bf16 v[6:9], v[228:231], v[200:203], v[6:9]
	v_mfma_f32_16x16x32_bf16 v[2:5], v[236:239], v[200:203], v[2:5]
	s_barrier
	v_add_u32 v152, s45, v1
	s_add_i32 s18, 0, 0x18000
	v_add_u32_e32 v152, s18, v152
	ds_read_b128 v[156:159], v152
	ds_read_b128 v[160:163], v152 offset:1024
	ds_read_b128 v[164:167], v152 offset:2048
	ds_read_b128 v[168:171], v152 offset:3072
	v_add_u32 v152, s44, v1
	s_add_u32 s42, s42, 0x40000
	v_add_u32_e32 v152, 0, v152
	s_addc_u32 s43, s43, 0
	s_mov_b32 m0, s12
	ds_read_b128 v[172:175], v152 offset:32768
	ds_read_b128 v[176:179], v152 offset:33792
	ds_read_b128 v[180:183], v152 offset:34816
	ds_read_b128 v[184:187], v152 offset:35840
	ds_read_b128 v[188:191], v152 offset:36864
	ds_read_b128 v[192:195], v152 offset:37888
	ds_read_b128 v[196:199], v152 offset:38912
	ds_read_b128 v[200:203], v152 offset:39936
	v_lshl_add_u64 v[152:153], s[42:43], 0, v[136:137]
	global_load_lds_dwordx4 v[152:153], off
	v_lshl_add_u64 v[152:153], s[42:43], 0, v[132:133]
	s_mov_b32 m0, s13
	s_nop 0
	global_load_lds_dwordx4 v[152:153], off
	s_waitcnt lgkmcnt(8)
	s_barrier
	s_waitcnt lgkmcnt(0)
	s_waitcnt lgkmcnt(0)
	v_mfma_f32_16x16x32_bf16 v[126:129], v[156:159], v[172:175], v[126:129]
	v_mfma_f32_16x16x32_bf16 v[122:125], v[164:167], v[172:175], v[122:125]
	v_mfma_f32_16x16x32_bf16 v[118:121], v[156:159], v[180:183], v[118:121]
	v_mfma_f32_16x16x32_bf16 v[114:117], v[164:167], v[180:183], v[114:117]
	v_mfma_f32_16x16x32_bf16 v[102:105], v[156:159], v[188:191], v[102:105]
	v_mfma_f32_16x16x32_bf16 v[98:101], v[164:167], v[188:191], v[98:101]
	v_mfma_f32_16x16x32_bf16 v[86:89], v[156:159], v[196:199], v[86:89]
	v_mfma_f32_16x16x32_bf16 v[82:85], v[164:167], v[196:199], v[82:85]
	v_mfma_f32_16x16x32_bf16 v[126:129], v[160:163], v[176:179], v[126:129]
	v_mfma_f32_16x16x32_bf16 v[122:125], v[168:171], v[176:179], v[122:125]
	v_mfma_f32_16x16x32_bf16 v[118:121], v[160:163], v[184:187], v[118:121]
	v_mfma_f32_16x16x32_bf16 v[114:117], v[168:171], v[184:187], v[114:117]
	v_mfma_f32_16x16x32_bf16 v[102:105], v[160:163], v[192:195], v[102:105]
	v_mfma_f32_16x16x32_bf16 v[98:101], v[168:171], v[192:195], v[98:101]
	v_mfma_f32_16x16x32_bf16 v[86:89], v[160:163], v[200:203], v[86:89]
	v_mfma_f32_16x16x32_bf16 v[82:85], v[168:171], v[200:203], v[82:85]
	s_barrier
	v_add_u32 v152, s45, v1
	s_add_i32 s19, 0, 0x1c000
	s_add_i32 s18, s18, s10
	v_add_u32_e32 v152, s19, v152
	v_lshl_add_u64 v[144:145], v[144:145], 0, s[30:31]
	s_mov_b32 m0, s18
	ds_read_b128 v[224:227], v152
	ds_read_b128 v[228:231], v152 offset:1024
	ds_read_b128 v[232:235], v152 offset:2048
	ds_read_b128 v[236:239], v152 offset:3072
	global_load_lds_dwordx4 v[144:145], off
	v_lshl_add_u64 v[144:145], v[146:147], 0, s[30:31]
	s_add_i32 m0, s18, 0x2000
	s_nop 0
	global_load_lds_dwordx4 v[144:145], off
	s_barrier
	s_waitcnt lgkmcnt(0)
	s_waitcnt lgkmcnt(0)
	v_mfma_f32_16x16x32_bf16 v[110:113], v[224:227], v[172:175], v[110:113]
	v_mfma_f32_16x16x32_bf16 v[106:109], v[232:235], v[172:175], v[106:109]
	v_mfma_f32_16x16x32_bf16 v[94:97], v[224:227], v[180:183], v[94:97]
	v_mfma_f32_16x16x32_bf16 v[90:93], v[232:235], v[180:183], v[90:93]
	v_mfma_f32_16x16x32_bf16 v[78:81], v[224:227], v[188:191], v[78:81]
	v_mfma_f32_16x16x32_bf16 v[74:77], v[232:235], v[188:191], v[74:77]
	v_mfma_f32_16x16x32_bf16 v[70:73], v[224:227], v[196:199], v[70:73]
	v_mfma_f32_16x16x32_bf16 v[66:69], v[232:235], v[196:199], v[66:69]
	v_mfma_f32_16x16x32_bf16 v[110:113], v[228:231], v[176:179], v[110:113]
	v_mfma_f32_16x16x32_bf16 v[106:109], v[236:239], v[176:179], v[106:109]
	v_mfma_f32_16x16x32_bf16 v[94:97], v[228:231], v[184:187], v[94:97]
	v_mfma_f32_16x16x32_bf16 v[90:93], v[236:239], v[184:187], v[90:93]
	v_mfma_f32_16x16x32_bf16 v[78:81], v[228:231], v[192:195], v[78:81]
	v_mfma_f32_16x16x32_bf16 v[74:77], v[236:239], v[192:195], v[74:77]
	v_mfma_f32_16x16x32_bf16 v[70:73], v[228:231], v[200:203], v[70:73]
	v_mfma_f32_16x16x32_bf16 v[66:69], v[236:239], v[200:203], v[66:69]
	s_barrier
; #define PG8_STAGE(bufoff, gbase, voff) do { _Pragma("unroll") for (int _i = 0; _i < 2; ++_i) \
;         __builtin_amdgcn_global_load_lds((const unsigned*)((const char*)(gbase) + (voff)[_i]), (PG8_LAS unsigned*)(lds + (bufoff) + ldsw + _i * 8192), 16, 0, 0); } while (0)
; #define PG8_LDA(dst, b, h) do { int aoff; asm volatile("v_add_u32 %0, %1, %2" : "=v"(aoff) : "s"(ua), "v"(foff)); _Pragma("unroll") for (int m = 0; m < 4; ++m) _Pragma("unroll") for (int k = 0; k < 2; ++k) dst[m][k] = *(const PG8_LAS bf16x8*)(lds + PG8_SA(b, h) + aoff + m * 2048 + k * 1024); } while (0)
; #define PG8_MMA(ai, bj, At, Bt) do { __builtin_amdgcn_s_setprio(1); _Pragma("unroll") for (int m = 0; m < 4; ++m) _Pragma("unroll") for (int n = 0; n < 2; ++n) _Pragma("unroll") for (int k = 0; k < 2; ++k) \
;         acc[ai][bj][m][n] = __builtin_amdgcn_mfma_f32_16x16x32_bf16(Bt[n][k], At[m][k], acc[ai][bj][m][n], 0, 0, 0); __builtin_amdgcn_s_setprio(0); } while (0)
; #define PG8_WAIT_V(n) asm volatile("s_waitcnt vmcnt(" #n ")" ::: "memory")
; #define PG8_WAIT_L(n) asm volatile("s_waitcnt lgkmcnt(" #n ")" ::: "memory")
; #define PG8_BAR __builtin_amdgcn_s_barrier()
; #define PG8_SCHED __builtin_amdgcn_sched_barrier(0)
; template <class Epi, class Sched>
; __device__ __forceinline__ void gemm_phase(PG8_LAS unsigned char* lds, const Gemm g, const Sched& S, const Epi& E) {
;     ...
;             PG8_LDA(At, 1, 1); PG8_STAGE(PG8_SA(1, 0), a3, voffA);
;             PG8_BAR; PG8_WAIT_L(0); PG8_MMA(1, 0, At, B0); PG8_BAR; PG8_SCHED;
;             PG8_STAGE(PG8_SB(1, 1), b3 + hstep, voffB);
;             PG8_WAIT_V(6); PG8_BAR; PG8_MMA(1, 1, At, B1); PG8_BAR;
	v_add_u32 v144, s44, v1
	s_mov_b32 m0, s46
	v_add_u32_e32 v144, 0, v144
	ds_read_b128 v[172:175], v144 offset:49152
	ds_read_b128 v[176:179], v144 offset:50176
	ds_read_b128 v[180:183], v144 offset:51200
	ds_read_b128 v[184:187], v144 offset:52224
	ds_read_b128 v[188:191], v144 offset:53248
	ds_read_b128 v[192:195], v144 offset:54272
	ds_read_b128 v[196:199], v144 offset:55296
	ds_read_b128 v[200:203], v144 offset:56320
	v_lshl_add_u64 v[144:145], v[148:149], 0, s[30:31]
	global_load_lds_dwordx4 v[144:145], off
	v_lshl_add_u64 v[144:145], v[150:151], 0, s[30:31]
	s_mov_b32 m0, s47
	s_nop 0
	global_load_lds_dwordx4 v[144:145], off
	s_barrier
	s_waitcnt lgkmcnt(0)
	s_waitcnt lgkmcnt(0)
	v_mfma_f32_16x16x32_bf16 v[62:65], v[156:159], v[172:175], v[62:65]
	v_mfma_f32_16x16x32_bf16 v[58:61], v[164:167], v[172:175], v[58:61]
	v_mfma_f32_16x16x32_bf16 v[54:57], v[156:159], v[180:183], v[54:57]
	v_mfma_f32_16x16x32_bf16 v[50:53], v[164:167], v[180:183], v[50:53]
	v_mfma_f32_16x16x32_bf16 v[38:41], v[156:159], v[188:191], v[38:41]
	v_mfma_f32_16x16x32_bf16 v[34:37], v[164:167], v[188:191], v[34:37]
	v_mfma_f32_16x16x32_bf16 v[22:25], v[156:159], v[196:199], v[22:25]
	v_mfma_f32_16x16x32_bf16 v[18:21], v[164:167], v[196:199], v[18:21]
	v_mfma_f32_16x16x32_bf16 v[62:65], v[160:163], v[176:179], v[62:65]
	v_mfma_f32_16x16x32_bf16 v[58:61], v[168:171], v[176:179], v[58:61]
	v_mfma_f32_16x16x32_bf16 v[54:57], v[160:163], v[184:187], v[54:57]
	v_mfma_f32_16x16x32_bf16 v[50:53], v[168:171], v[184:187], v[50:53]
	v_mfma_f32_16x16x32_bf16 v[38:41], v[160:163], v[192:195], v[38:41]
	v_mfma_f32_16x16x32_bf16 v[34:37], v[168:171], v[192:195], v[34:37]
	v_mfma_f32_16x16x32_bf16 v[22:25], v[160:163], v[200:203], v[22:25]
	v_mfma_f32_16x16x32_bf16 v[18:21], v[168:171], v[200:203], v[18:21]
	s_barrier
	s_add_u32 s40, s40, 0x40080
	s_addc_u32 s41, s41, 0
	s_add_i32 s18, s19, s10
	v_lshl_add_u64 v[144:145], s[40:41], 0, v[134:135]
	s_mov_b32 m0, s18
	s_nop 0
	global_load_lds_dwordx4 v[144:145], off
	v_lshl_add_u64 v[144:145], s[40:41], 0, v[130:131]
	s_add_i32 m0, s18, 0x2000
	s_nop 0
	global_load_lds_dwordx4 v[144:145], off
	s_waitcnt vmcnt(6)
	s_barrier
	v_mfma_f32_16x16x32_bf16 v[46:49], v[224:227], v[172:175], v[46:49]
	v_mfma_f32_16x16x32_bf16 v[42:45], v[232:235], v[172:175], v[42:45]
	v_mfma_f32_16x16x32_bf16 v[30:33], v[224:227], v[180:183], v[30:33]
	v_mfma_f32_16x16x32_bf16 v[26:29], v[232:235], v[180:183], v[26:29]
	v_mfma_f32_16x16x32_bf16 v[14:17], v[224:227], v[188:191], v[14:17]
	v_mfma_f32_16x16x32_bf16 v[10:13], v[232:235], v[188:191], v[10:13]
	v_mfma_f32_16x16x32_bf16 v[6:9], v[224:227], v[196:199], v[6:9]
	v_mfma_f32_16x16x32_bf16 v[2:5], v[232:235], v[196:199], v[2:5]
	v_mfma_f32_16x16x32_bf16 v[46:49], v[228:231], v[176:179], v[46:49]
	v_mfma_f32_16x16x32_bf16 v[42:45], v[236:239], v[176:179], v[42:45]
	v_mfma_f32_16x16x32_bf16 v[30:33], v[228:231], v[184:187], v[30:33]
	v_mfma_f32_16x16x32_bf16 v[26:29], v[236:239], v[184:187], v[26:29]
	v_mfma_f32_16x16x32_bf16 v[14:17], v[228:231], v[192:195], v[14:17]
	v_mfma_f32_16x16x32_bf16 v[10:13], v[236:239], v[192:195], v[10:13]
	v_mfma_f32_16x16x32_bf16 v[6:9], v[228:231], v[200:203], v[6:9]
	v_mfma_f32_16x16x32_bf16 v[2:5], v[236:239], v[200:203], v[2:5]
	s_add_i32 s54, s54, 2
	s_add_u32 s28, s28, 0x100
	s_addc_u32 s29, s29, 0
	s_add_u32 s52, s52, 0x100
	s_addc_u32 s53, s53, 0
	s_cmp_gt_u32 s54, 13
	s_barrier
	s_cbranch_scc0 .LBB0_478
; __device__ __forceinline__ unsigned cvt_pk_bf16(float lo, float hi) { const f32x2c f = {lo, hi}; return __builtin_bit_cast(unsigned, __builtin_convertvector(f, bf16x2c)); }
;     __device__ __forceinline__ void operator()(const f32x4 (&acc)[2][2][4][2], const Unit& u, int wr, int wc, int fr, int fq) const {
;         const int row0 = u.pm * BM + wr * 64 + fr; const int col0 = u.pn * BM + wc * 32 + 8 * fq;
; #pragma unroll
;         for (int ai = 0; ai < 2; ++ai)
; #pragma unroll
;             for (int m = 0; m < 4; ++m) { bf16_t* rowp = O + (size_t)(row0 + ai * HALF + m * 16) * ldc + col0;
; #pragma unroll
;                 for (int bj = 0; bj < 2; ++bj) { const f32x4 v0 = acc[ai][bj][m][0], v1 = acc[ai][bj][m][1];
;                     u32x4 w; w.x = cvt_pk_bf16(v0[0], v0[1]); w.y = cvt_pk_bf16(v0[2], v0[3]); w.z = cvt_pk_bf16(v1[0], v1[1]); w.w = cvt_pk_bf16(v1[2], v1[3]);
;                     *(u32x4*)(rowp + bj * HALF) = w; } }
	v_lshl_add_u32 v150, s2, 8, v142
	v_lshl_or_b32 v144, s49, 8, v143
	v_ashrrev_i32_e32 v145, 31, v144
	v_mov_b64_e32 v[146:147], s[68:69]
	v_cvt_pk_bf16_f32 v70, v70, v71
	v_cvt_pk_bf16_f32 v71, v72, v73
	v_cvt_pk_bf16_f32 v72, v66, v67
	v_add_u32_e32 v66, 0x80, v150
	v_mad_i64_i32 v[148:149], s[28:29], v150, s90, v[146:147]
	v_lshlrev_b64 v[144:145], 1, v[144:145]
	v_cvt_pk_bf16_f32 v110, v110, v111
	v_cvt_pk_bf16_f32 v111, v112, v113
	v_cvt_pk_bf16_f32 v112, v106, v107
	v_or_b32_e32 v106, 16, v150
	v_mad_i64_i32 v[66:67], s[28:29], v66, s90, v[146:147]
	v_cvt_pk_bf16_f32 v46, v46, v47
	v_cvt_pk_bf16_f32 v47, v48, v49
	v_cvt_pk_bf16_f32 v48, v42, v43
	v_add_u32_e32 v42, 0x90, v150
	v_lshl_add_u64 v[148:149], v[148:149], 0, v[144:145]
	v_cvt_pk_bf16_f32 v113, v108, v109
	v_mad_i64_i32 v[106:107], s[28:29], v106, s90, v[146:147]
	v_cvt_pk_bf16_f32 v94, v94, v95
	v_cvt_pk_bf16_f32 v95, v96, v97
	v_cvt_pk_bf16_f32 v96, v90, v91
	v_or_b32_e32 v90, 32, v150
	v_lshl_add_u64 v[66:67], v[66:67], 0, v[144:145]
	v_cvt_pk_bf16_f32 v49, v44, v45
	v_mad_i64_i32 v[42:43], s[28:29], v42, s90, v[146:147]
	v_cvt_pk_bf16_f32 v30, v30, v31
	v_cvt_pk_bf16_f32 v31, v32, v33
	v_cvt_pk_bf16_f32 v32, v26, v27
	v_add_u32_e32 v26, 0xa0, v150
	global_store_dwordx4 v[148:149], v[110:113], off offset:256
	v_cvt_pk_bf16_f32 v97, v92, v93
	v_mad_i64_i32 v[90:91], s[28:29], v90, s90, v[146:147]
	v_lshl_add_u64 v[110:111], v[106:107], 0, v[144:145]
	v_cvt_pk_bf16_f32 v78, v78, v79
	v_cvt_pk_bf16_f32 v79, v80, v81
	v_cvt_pk_bf16_f32 v80, v74, v75
	v_or_b32_e32 v74, 48, v150
	global_store_dwordx4 v[66:67], v[46:49], off offset:256
	v_cvt_pk_bf16_f32 v33, v28, v29
	v_mad_i64_i32 v[26:27], s[28:29], v26, s90, v[146:147]
	v_lshl_add_u64 v[46:47], v[42:43], 0, v[144:145]
	v_cvt_pk_bf16_f32 v14, v14, v15
	v_cvt_pk_bf16_f32 v15, v16, v17
	v_cvt_pk_bf16_f32 v16, v10, v11
	v_add_u32_e32 v10, 0xb0, v150
	global_store_dwordx4 v[110:111], v[94:97], off offset:256
	v_cvt_pk_bf16_f32 v81, v76, v77
	v_mad_i64_i32 v[74:75], s[28:29], v74, s90, v[146:147]
	v_lshl_add_u64 v[94:95], v[90:91], 0, v[144:145]
	global_store_dwordx4 v[46:47], v[30:33], off offset:256
	v_cvt_pk_bf16_f32 v17, v12, v13
	v_mad_i64_i32 v[10:11], s[28:29], v10, s90, v[146:147]
	v_lshl_add_u64 v[30:31], v[26:27], 0, v[144:145]
	v_cvt_pk_bf16_f32 v126, v126, v127
	v_cvt_pk_bf16_f32 v127, v128, v129
	v_cvt_pk_bf16_f32 v128, v122, v123
	v_cvt_pk_bf16_f32 v129, v124, v125
	v_cvt_pk_bf16_f32 v106, v118, v119
	v_cvt_pk_bf16_f32 v107, v120, v121
	v_cvt_pk_bf16_f32 v108, v114, v115
	v_cvt_pk_bf16_f32 v109, v116, v117
	v_cvt_pk_bf16_f32 v90, v102, v103
	v_cvt_pk_bf16_f32 v91, v104, v105
	v_cvt_pk_bf16_f32 v92, v98, v99
	v_cvt_pk_bf16_f32 v93, v100, v101
	global_store_dwordx4 v[94:95], v[78:81], off offset:256
	v_cvt_pk_bf16_f32 v76, v82, v83
	v_cvt_pk_bf16_f32 v77, v84, v85
	v_lshl_add_u64 v[78:79], v[74:75], 0, v[144:145]
	v_cvt_pk_bf16_f32 v74, v86, v87
	v_cvt_pk_bf16_f32 v75, v88, v89
	v_cvt_pk_bf16_f32 v73, v68, v69
	v_cvt_pk_bf16_f32 v62, v62, v63
	v_cvt_pk_bf16_f32 v63, v64, v65
	v_cvt_pk_bf16_f32 v64, v58, v59
	v_cvt_pk_bf16_f32 v65, v60, v61
	v_cvt_pk_bf16_f32 v42, v54, v55
	v_cvt_pk_bf16_f32 v43, v56, v57
	v_cvt_pk_bf16_f32 v44, v50, v51
	v_cvt_pk_bf16_f32 v45, v52, v53
	v_cvt_pk_bf16_f32 v26, v38, v39
	v_cvt_pk_bf16_f32 v27, v40, v41
	v_cvt_pk_bf16_f32 v28, v34, v35
	v_cvt_pk_bf16_f32 v29, v36, v37
	global_store_dwordx4 v[30:31], v[14:17], off offset:256
	v_cvt_pk_bf16_f32 v12, v18, v19
	v_cvt_pk_bf16_f32 v13, v20, v21
	v_lshl_add_u64 v[14:15], v[10:11], 0, v[144:145]
	v_cvt_pk_bf16_f32 v10, v22, v23
	v_cvt_pk_bf16_f32 v11, v24, v25
	v_cvt_pk_bf16_f32 v6, v6, v7
	v_cvt_pk_bf16_f32 v7, v8, v9
	v_cvt_pk_bf16_f32 v8, v2, v3
	v_cvt_pk_bf16_f32 v9, v4, v5
	s_and_b64 vcc, exec, s[38:39]
	s_mov_b32 s49, s16
	s_mov_b32 s2, s20
	s_mov_b64 s[40:41], s[26:27]
	s_mov_b64 s[28:29], s[24:25]
	global_store_dwordx4 v[148:149], v[126:129], off
	global_store_dwordx4 v[110:111], v[106:109], off
	global_store_dwordx4 v[94:95], v[90:93], off
	global_store_dwordx4 v[78:79], v[74:77], off
	global_store_dwordx4 v[78:79], v[70:73], off offset:256
	global_store_dwordx4 v[66:67], v[62:65], off
	global_store_dwordx4 v[46:47], v[42:45], off
	global_store_dwordx4 v[30:31], v[26:29], off
	global_store_dwordx4 v[14:15], v[10:13], off
	global_store_dwordx4 v[14:15], v[6:9], off offset:256
	s_cbranch_vccz .LBB0_475
	s_waitcnt vmcnt(0)
	s_cmpk_gt_u32 s7, 0xff
	s_cbranch_scc1 .LBB0_482
	s_barrier

; #define PG8_STAGE(bufoff, gbase, voff) do { _Pragma("unroll") for (int _i = 0; _i < 2; ++_i) \
;         __builtin_amdgcn_global_load_lds((const unsigned*)((const char*)(gbase) + (voff)[_i]), (PG8_LAS unsigned*)(lds + (bufoff) + ldsw + _i * 8192), 16, 0, 0); } while (0)
; #define PG8_LDA(dst, b, h) do { int aoff; asm volatile("v_add_u32 %0, %1, %2" : "=v"(aoff) : "s"(ua), "v"(foff)); _Pragma("unroll") for (int m = 0; m < 4; ++m) _Pragma("unroll") for (int k = 0; k < 2; ++k) dst[m][k] = *(const PG8_LAS bf16x8*)(lds + PG8_SA(b, h) + aoff + m * 2048 + k * 1024); } while (0)
; #define PG8_LDB(dst, b, h) do { int boff; asm volatile("v_add_u32 %0, %1, %2" : "=v"(boff) : "s"(ub), "v"(foff)); _Pragma("unroll") for (int n = 0; n < 2; ++n) _Pragma("unroll") for (int k = 0; k < 2; ++k) dst[n][k] = *(const PG8_LAS bf16x8*)(lds + PG8_SB(b, h) + boff + n * 2048 + k * 1024); } while (0)
; #define PG8_MMA(ai, bj, At, Bt) do { __builtin_amdgcn_s_setprio(1); _Pragma("unroll") for (int m = 0; m < 4; ++m) _Pragma("unroll") for (int n = 0; n < 2; ++n) _Pragma("unroll") for (int k = 0; k < 2; ++k) \
;         acc[ai][bj][m][n] = __builtin_amdgcn_mfma_f32_16x16x32_bf16(Bt[n][k], At[m][k], acc[ai][bj][m][n], 0, 0, 0); __builtin_amdgcn_s_setprio(0); } while (0)
; #define PG8_WAIT_L(n) asm volatile("s_waitcnt lgkmcnt(" #n ")" ::: "memory")
; #define PG8_BAR __builtin_amdgcn_s_barrier()
; template <class Epi, class Sched>
; __device__ __forceinline__ void gemm_phase(PG8_LAS unsigned char* lds, const Gemm g, const Sched& S, const Epi& E) {
;     ...
;             const bool last = (t == cnt - 2);
;             const char* a1 = cA + (size_t)(t + 1) * kstep;
;             const char* a2 = last ? nA : cA + (size_t)(t + 2) * kstep; const char* b2 = last ? nB : cB + (size_t)(t + 2) * kstep;
;             const char* a3 = a2 + kstep; const char* b3 = b2 + kstep;
;             if (last && has_next) S.a_ready(nxt);
;             PG8_LDB(B0, 0, 0); PG8_SCHED; PG8_LDA(At, 0, 0); PG8_STAGE(PG8_SA(1, 1), a1 + hstep, voffA);
;             PG8_WAIT_L(8); PG8_BAR; PG8_WAIT_L(0); PG8_MMA(0, 0, At, B0); PG8_BAR; PG8_SCHED;
;             PG8_LDB(B1, 0, 1); PG8_STAGE(PG8_SB(0, 0), b2, voffB);
;             PG8_BAR; PG8_WAIT_L(0); PG8_MMA(0, 1, At, B1); PG8_BAR;
;             PG8_LDA(At, 0, 1); PG8_STAGE(PG8_SA(0, 0), a2, voffA);
;             PG8_BAR; PG8_WAIT_L(0); PG8_MMA(1, 0, At, B0); PG8_BAR; PG8_SCHED;
.LBB0_658:
	s_add_i32 s43, s20, 2
	s_add_u32 s16, s2, 0x100
	s_addc_u32 s17, s3, 0
	s_add_i32 s18, 0, 0x10000
	v_add_u32 v138, s52, v1
	s_cmp_eq_u32 s40, s20
	v_add_u32_e32 v146, s18, v138
	ds_read_b128 v[138:141], v146
	ds_read_b128 v[142:145], v146 offset:1024
	ds_read_b128 v[156:159], v146 offset:2048
	ds_read_b128 v[160:163], v146 offset:3072
	s_cselect_b32 s20, s48, s41
	s_cselect_b32 s27, s45, s17
	s_cselect_b32 s26, s44, s16
	s_cselect_b32 s21, s49, s42
	v_add_u32 v146, s29, v1
	s_add_i32 m0, s11, 0xc000
	v_add_u32_e32 v146, 0, v146
	ds_read_b128 v[164:167], v146
	ds_read_b128 v[168:171], v146 offset:1024
	ds_read_b128 v[172:175], v146 offset:2048
	ds_read_b128 v[176:179], v146 offset:3072
	ds_read_b128 v[180:183], v146 offset:4096
	ds_read_b128 v[184:187], v146 offset:5120
	ds_read_b128 v[188:191], v146 offset:6144
	ds_read_b128 v[192:195], v146 offset:7168
	v_lshl_add_u64 v[146:147], s[2:3], 0, v[134:135]
	global_load_lds_dwordx4 v[146:147], off
	v_lshl_add_u64 v[146:147], s[2:3], 0, v[136:137]
	s_add_i32 m0, s11, 0xe000
	s_nop 0
	global_load_lds_dwordx4 v[146:147], off
	s_waitcnt lgkmcnt(8)
	s_barrier
	s_waitcnt lgkmcnt(0)
	s_waitcnt lgkmcnt(0)
	v_mfma_f32_16x16x32_bf16 v[126:129], v[138:141], v[164:167], v[126:129]
	v_mfma_f32_16x16x32_bf16 v[118:121], v[156:159], v[164:167], v[118:121]
	v_mfma_f32_16x16x32_bf16 v[110:113], v[138:141], v[172:175], v[110:113]
	v_mfma_f32_16x16x32_bf16 v[102:105], v[156:159], v[172:175], v[102:105]
	v_mfma_f32_16x16x32_bf16 v[94:97], v[138:141], v[180:183], v[94:97]
	v_mfma_f32_16x16x32_bf16 v[86:89], v[156:159], v[180:183], v[86:89]
	v_mfma_f32_16x16x32_bf16 v[78:81], v[138:141], v[188:191], v[78:81]
	v_mfma_f32_16x16x32_bf16 v[70:73], v[156:159], v[188:191], v[70:73]
	v_mfma_f32_16x16x32_bf16 v[126:129], v[142:145], v[168:171], v[126:129]
	v_mfma_f32_16x16x32_bf16 v[118:121], v[160:163], v[168:171], v[118:121]
	v_mfma_f32_16x16x32_bf16 v[110:113], v[142:145], v[176:179], v[110:113]
	v_mfma_f32_16x16x32_bf16 v[102:105], v[160:163], v[176:179], v[102:105]
	v_mfma_f32_16x16x32_bf16 v[94:97], v[142:145], v[184:187], v[94:97]
	v_mfma_f32_16x16x32_bf16 v[86:89], v[160:163], v[184:187], v[86:89]
	v_mfma_f32_16x16x32_bf16 v[78:81], v[142:145], v[192:195], v[78:81]
	v_mfma_f32_16x16x32_bf16 v[70:73], v[160:163], v[192:195], v[70:73]
	s_barrier
	v_add_u32 v146, s52, v1
	s_add_i32 s19, 0, 0x14000
	v_add_u32_e32 v146, s19, v146
	s_add_i32 s2, s18, s10
	ds_read_b128 v[196:199], v146
	ds_read_b128 v[200:203], v146 offset:1024
	ds_read_b128 v[224:227], v146 offset:2048
	ds_read_b128 v[228:231], v146 offset:3072
	v_lshl_add_u64 v[146:147], s[20:21], 0, v[130:131]
	s_mov_b32 m0, s2
	v_lshl_add_u64 v[148:149], s[20:21], 0, v[132:133]
	global_load_lds_dwordx4 v[146:147], off
	s_add_i32 m0, s2, 0x2000
	s_nop 0
	global_load_lds_dwordx4 v[148:149], off
	s_barrier
	s_waitcnt lgkmcnt(0)
	s_waitcnt lgkmcnt(0)
	v_mfma_f32_16x16x32_bf16 v[122:125], v[196:199], v[164:167], v[122:125]
	v_mfma_f32_16x16x32_bf16 v[114:117], v[224:227], v[164:167], v[114:117]
	v_mfma_f32_16x16x32_bf16 v[106:109], v[196:199], v[172:175], v[106:109]
	v_mfma_f32_16x16x32_bf16 v[98:101], v[224:227], v[172:175], v[98:101]
	v_mfma_f32_16x16x32_bf16 v[90:93], v[196:199], v[180:183], v[90:93]
	v_mfma_f32_16x16x32_bf16 v[82:85], v[224:227], v[180:183], v[82:85]
	v_mfma_f32_16x16x32_bf16 v[74:77], v[196:199], v[188:191], v[74:77]
	v_mfma_f32_16x16x32_bf16 v[66:69], v[224:227], v[188:191], v[66:69]
	v_mfma_f32_16x16x32_bf16 v[122:125], v[200:203], v[168:171], v[122:125]
	v_mfma_f32_16x16x32_bf16 v[114:117], v[228:231], v[168:171], v[114:117]
	v_mfma_f32_16x16x32_bf16 v[106:109], v[200:203], v[176:179], v[106:109]
	v_mfma_f32_16x16x32_bf16 v[98:101], v[228:231], v[176:179], v[98:101]
	v_mfma_f32_16x16x32_bf16 v[90:93], v[200:203], v[184:187], v[90:93]
	v_mfma_f32_16x16x32_bf16 v[82:85], v[228:231], v[184:187], v[82:85]
	v_mfma_f32_16x16x32_bf16 v[74:77], v[200:203], v[192:195], v[74:77]
	v_mfma_f32_16x16x32_bf16 v[66:69], v[228:231], v[192:195], v[66:69]
	s_barrier
	v_add_u32 v150, s29, v1
	s_mov_b32 m0, s11
	v_add_u32_e32 v150, 0, v150
	ds_read_b128 v[164:167], v150 offset:16384
	ds_read_b128 v[168:171], v150 offset:17408
	ds_read_b128 v[172:175], v150 offset:18432
	ds_read_b128 v[176:179], v150 offset:19456
	ds_read_b128 v[180:183], v150 offset:20480
	ds_read_b128 v[184:187], v150 offset:21504
	ds_read_b128 v[188:191], v150 offset:22528
	ds_read_b128 v[192:195], v150 offset:23552
	v_lshl_add_u64 v[150:151], s[26:27], 0, v[130:131]
	global_load_lds_dwordx4 v[150:151], off
	v_lshl_add_u64 v[152:153], s[26:27], 0, v[132:133]
	s_mov_b32 m0, s12
	s_nop 0
	global_load_lds_dwordx4 v[152:153], off
	s_barrier
	s_waitcnt lgkmcnt(0)
	s_waitcnt lgkmcnt(0)
	v_mfma_f32_16x16x32_bf16 v[62:65], v[138:141], v[164:167], v[62:65]
	v_mfma_f32_16x16x32_bf16 v[54:57], v[156:159], v[164:167], v[54:57]
	v_mfma_f32_16x16x32_bf16 v[46:49], v[138:141], v[172:175], v[46:49]
	v_mfma_f32_16x16x32_bf16 v[38:41], v[156:159], v[172:175], v[38:41]
	v_mfma_f32_16x16x32_bf16 v[30:33], v[138:141], v[180:183], v[30:33]
	v_mfma_f32_16x16x32_bf16 v[22:25], v[156:159], v[180:183], v[22:25]
	v_mfma_f32_16x16x32_bf16 v[14:17], v[138:141], v[188:191], v[14:17]
	v_mfma_f32_16x16x32_bf16 v[6:9], v[156:159], v[188:191], v[6:9]
	v_mfma_f32_16x16x32_bf16 v[62:65], v[142:145], v[168:171], v[62:65]
	v_mfma_f32_16x16x32_bf16 v[54:57], v[160:163], v[168:171], v[54:57]
	v_mfma_f32_16x16x32_bf16 v[46:49], v[142:145], v[176:179], v[46:49]
	v_mfma_f32_16x16x32_bf16 v[38:41], v[160:163], v[176:179], v[38:41]
	v_mfma_f32_16x16x32_bf16 v[30:33], v[142:145], v[184:187], v[30:33]
	v_mfma_f32_16x16x32_bf16 v[22:25], v[160:163], v[184:187], v[22:25]
	v_mfma_f32_16x16x32_bf16 v[14:17], v[142:145], v[192:195], v[14:17]
	v_mfma_f32_16x16x32_bf16 v[6:9], v[160:163], v[192:195], v[6:9]
	s_barrier
; #define PG8_STAGE(bufoff, gbase, voff) do { _Pragma("unroll") for (int _i = 0; _i < 2; ++_i) \
;         __builtin_amdgcn_global_load_lds((const unsigned*)((const char*)(gbase) + (voff)[_i]), (PG8_LAS unsigned*)(lds + (bufoff) + ldsw + _i * 8192), 16, 0, 0); } while (0)
; #define PG8_LDA(dst, b, h) do { int aoff; asm volatile("v_add_u32 %0, %1, %2" : "=v"(aoff) : "s"(ua), "v"(foff)); _Pragma("unroll") for (int m = 0; m < 4; ++m) _Pragma("unroll") for (int k = 0; k < 2; ++k) dst[m][k] = *(const PG8_LAS bf16x8*)(lds + PG8_SA(b, h) + aoff + m * 2048 + k * 1024); } while (0)
; #define PG8_LDB(dst, b, h) do { int boff; asm volatile("v_add_u32 %0, %1, %2" : "=v"(boff) : "s"(ub), "v"(foff)); _Pragma("unroll") for (int n = 0; n < 2; ++n) _Pragma("unroll") for (int k = 0; k < 2; ++k) dst[n][k] = *(const PG8_LAS bf16x8*)(lds + PG8_SB(b, h) + boff + n * 2048 + k * 1024); } while (0)
; #define PG8_MMA(ai, bj, At, Bt) do { __builtin_amdgcn_s_setprio(1); _Pragma("unroll") for (int m = 0; m < 4; ++m) _Pragma("unroll") for (int n = 0; n < 2; ++n) _Pragma("unroll") for (int k = 0; k < 2; ++k) \
;         acc[ai][bj][m][n] = __builtin_amdgcn_mfma_f32_16x16x32_bf16(Bt[n][k], At[m][k], acc[ai][bj][m][n], 0, 0, 0); __builtin_amdgcn_s_setprio(0); } while (0)
; #define PG8_WAIT_V(n) asm volatile("s_waitcnt vmcnt(" #n ")" ::: "memory")
; #define PG8_WAIT_L(n) asm volatile("s_waitcnt lgkmcnt(" #n ")" ::: "memory")
; #define PG8_BAR __builtin_amdgcn_s_barrier()
; #define PG8_SCHED __builtin_amdgcn_sched_barrier(0)
; template <class Epi, class Sched>
; __device__ __forceinline__ void gemm_phase(PG8_LAS unsigned char* lds, const Gemm g, const Sched& S, const Epi& E) {
;     ...
;             PG8_STAGE(PG8_SB(0, 1), b2 + hstep, voffB);
;             PG8_WAIT_V(6); PG8_BAR; PG8_MMA(1, 1, At, B1); PG8_BAR;
;             PG8_LDB(B0, 1, 0); PG8_SCHED; PG8_LDA(At, 1, 0); PG8_STAGE(PG8_SA(0, 1), a2 + hstep, voffA);
;             PG8_WAIT_L(8); PG8_BAR; PG8_WAIT_L(0); PG8_MMA(0, 0, At, B0); PG8_BAR; PG8_SCHED;
;             PG8_LDB(B1, 1, 1); PG8_STAGE(PG8_SB(1, 0), b3, voffB);
	s_add_u32 s2, s20, 0x18000
	s_addc_u32 s3, s21, 0
	s_add_i32 s18, s19, s10
	v_lshl_add_u64 v[138:139], s[2:3], 0, v[130:131]
	s_mov_b32 m0, s18
	s_nop 0
	global_load_lds_dwordx4 v[138:139], off
	v_lshl_add_u64 v[138:139], s[2:3], 0, v[132:133]
	s_add_i32 m0, s18, 0x2000
	s_nop 0
	global_load_lds_dwordx4 v[138:139], off
	s_waitcnt vmcnt(6)
	s_barrier
	v_mfma_f32_16x16x32_bf16 v[58:61], v[196:199], v[164:167], v[58:61]
	v_mfma_f32_16x16x32_bf16 v[50:53], v[224:227], v[164:167], v[50:53]
	v_mfma_f32_16x16x32_bf16 v[42:45], v[196:199], v[172:175], v[42:45]
	v_mfma_f32_16x16x32_bf16 v[34:37], v[224:227], v[172:175], v[34:37]
	v_mfma_f32_16x16x32_bf16 v[26:29], v[196:199], v[180:183], v[26:29]
	v_mfma_f32_16x16x32_bf16 v[18:21], v[224:227], v[180:183], v[18:21]
	v_mfma_f32_16x16x32_bf16 v[10:13], v[196:199], v[188:191], v[10:13]
	v_mfma_f32_16x16x32_bf16 v[2:5], v[224:227], v[188:191], v[2:5]
	v_mfma_f32_16x16x32_bf16 v[58:61], v[200:203], v[168:171], v[58:61]
	v_mfma_f32_16x16x32_bf16 v[50:53], v[228:231], v[168:171], v[50:53]
	v_mfma_f32_16x16x32_bf16 v[42:45], v[200:203], v[176:179], v[42:45]
	v_mfma_f32_16x16x32_bf16 v[34:37], v[228:231], v[176:179], v[34:37]
	v_mfma_f32_16x16x32_bf16 v[26:29], v[200:203], v[184:187], v[26:29]
	v_mfma_f32_16x16x32_bf16 v[18:21], v[228:231], v[184:187], v[18:21]
	v_mfma_f32_16x16x32_bf16 v[10:13], v[200:203], v[192:195], v[10:13]
	v_mfma_f32_16x16x32_bf16 v[2:5], v[228:231], v[192:195], v[2:5]
	s_add_i32 s18, 0, 0x18000
	s_barrier
	v_add_u32 v138, s52, v1
	s_nop 0
	v_add_u32_e32 v160, s18, v138
	ds_read_b128 v[138:141], v160
	ds_read_b128 v[142:145], v160 offset:1024
	ds_read_b128 v[156:159], v160 offset:2048
	ds_read_b128 v[160:163], v160 offset:3072
	s_add_u32 s2, s26, 0x18000
	s_addc_u32 s3, s27, 0
	s_mov_b32 m0, s13
	v_add_u32 v164, s29, v1
	v_lshl_add_u64 v[196:197], s[2:3], 0, v[130:131]
	v_add_u32_e32 v192, 0, v164
	ds_read_b128 v[164:167], v192 offset:32768
	ds_read_b128 v[168:171], v192 offset:33792
	ds_read_b128 v[172:175], v192 offset:34816
	ds_read_b128 v[176:179], v192 offset:35840
	ds_read_b128 v[180:183], v192 offset:36864
	ds_read_b128 v[184:187], v192 offset:37888
	ds_read_b128 v[188:191], v192 offset:38912
	ds_read_b128 v[192:195], v192 offset:39936
	global_load_lds_dwordx4 v[196:197], off
	v_lshl_add_u64 v[196:197], s[2:3], 0, v[132:133]
	s_mov_b32 m0, s28
	s_nop 0
	global_load_lds_dwordx4 v[196:197], off
	s_waitcnt lgkmcnt(8)
	s_barrier
	s_waitcnt lgkmcnt(0)
	s_waitcnt lgkmcnt(0)
	v_mfma_f32_16x16x32_bf16 v[126:129], v[138:141], v[164:167], v[126:129]
	v_mfma_f32_16x16x32_bf16 v[118:121], v[156:159], v[164:167], v[118:121]
	v_mfma_f32_16x16x32_bf16 v[110:113], v[138:141], v[172:175], v[110:113]
	v_mfma_f32_16x16x32_bf16 v[102:105], v[156:159], v[172:175], v[102:105]
	v_mfma_f32_16x16x32_bf16 v[94:97], v[138:141], v[180:183], v[94:97]
	v_mfma_f32_16x16x32_bf16 v[86:89], v[156:159], v[180:183], v[86:89]
	v_mfma_f32_16x16x32_bf16 v[78:81], v[138:141], v[188:191], v[78:81]
	v_mfma_f32_16x16x32_bf16 v[70:73], v[156:159], v[188:191], v[70:73]
	v_mfma_f32_16x16x32_bf16 v[126:129], v[142:145], v[168:171], v[126:129]
	v_mfma_f32_16x16x32_bf16 v[118:121], v[160:163], v[168:171], v[118:121]
	v_mfma_f32_16x16x32_bf16 v[110:113], v[142:145], v[176:179], v[110:113]
	v_mfma_f32_16x16x32_bf16 v[102:105], v[160:163], v[176:179], v[102:105]
	v_mfma_f32_16x16x32_bf16 v[94:97], v[142:145], v[184:187], v[94:97]
	v_mfma_f32_16x16x32_bf16 v[86:89], v[160:163], v[184:187], v[86:89]
	v_mfma_f32_16x16x32_bf16 v[78:81], v[142:145], v[192:195], v[78:81]
	v_mfma_f32_16x16x32_bf16 v[70:73], v[160:163], v[192:195], v[70:73]
	s_barrier
	s_add_i32 s19, 0, 0x1c000
	s_add_i32 s2, s18, s10
	v_add_u32 v196, s52, v1
	v_lshl_add_u64 v[146:147], v[146:147], 0, s[30:31]
	v_add_u32_e32 v204, s19, v196
	s_mov_b32 m0, s2
	ds_read_b128 v[196:199], v204
	ds_read_b128 v[200:203], v204 offset:1024
	ds_read_b128 v[224:227], v204 offset:2048
	ds_read_b128 v[228:231], v204 offset:3072
	global_load_lds_dwordx4 v[146:147], off
	v_lshl_add_u64 v[146:147], v[148:149], 0, s[30:31]
	s_add_i32 m0, s2, 0x2000
	s_nop 0
	global_load_lds_dwordx4 v[146:147], off
	s_barrier
; #define PIN(i) ((const float*)(const GASP float*)karg_q(i))
; #define PG8_STAGE(bufoff, gbase, voff) do { _Pragma("unroll") for (int _i = 0; _i < 2; ++_i) \
;         __builtin_amdgcn_global_load_lds((const unsigned*)((const char*)(gbase) + (voff)[_i]), (PG8_LAS unsigned*)(lds + (bufoff) + ldsw + _i * 8192), 16, 0, 0); } while (0)
; #define PG8_LDA(dst, b, h) do { int aoff; asm volatile("v_add_u32 %0, %1, %2" : "=v"(aoff) : "s"(ua), "v"(foff)); _Pragma("unroll") for (int m = 0; m < 4; ++m) _Pragma("unroll") for (int k = 0; k < 2; ++k) dst[m][k] = *(const PG8_LAS bf16x8*)(lds + PG8_SA(b, h) + aoff + m * 2048 + k * 1024); } while (0)
; #define PG8_MMA(ai, bj, At, Bt) do { __builtin_amdgcn_s_setprio(1); _Pragma("unroll") for (int m = 0; m < 4; ++m) _Pragma("unroll") for (int n = 0; n < 2; ++n) _Pragma("unroll") for (int k = 0; k < 2; ++k) \
;         acc[ai][bj][m][n] = __builtin_amdgcn_mfma_f32_16x16x32_bf16(Bt[n][k], At[m][k], acc[ai][bj][m][n], 0, 0, 0); __builtin_amdgcn_s_setprio(0); } while (0)
; #define PG8_WAIT_V(n) asm volatile("s_waitcnt vmcnt(" #n ")" ::: "memory")
; #define PG8_BAR __builtin_amdgcn_s_barrier()
;     __device__ __forceinline__ void operator()(const f32x4 (&acc)[2][2][4][2], const Unit& u, int wr, int wc, int, int) const {
;     ...
;         const bool isq = u.pn < 3; const int head = (isq ? u.pn : u.pn - 3) * 2 + (wc >> 1), kind = wc & 1;
;         const bool latent = u.pm < 128, is_v = !isq && kind == 1, is_rope = isq && kind == 1, rot = is_rope && latent;
;         const int sbj = is_rope ? 8 : 32;
;         const float* gsrc = is_v ? (const float*)(ws + WS_ROPE) + 1024 : (isq ? PIN(16) + l * 96 : PIN(17) + l * 96);
;         const float* g = gsrc + (is_rope ? 64 + 16 * (fq & 1) : 8 * fq);
;         const float* rope = (const float*)(ws + WS_ROPE);
;         bf16_t* obase = (bf16_t*)(ws + (is_v ? WS_MV : (isq ? WS_MQ : WS_MK)));
; template <class Epi, class Sched>
; __device__ __forceinline__ void gemm_phase(PG8_LAS unsigned char* lds, const Gemm g, const Sched& S, const Epi& E) {
;     ...
;             PG8_BAR; PG8_WAIT_L(0); PG8_MMA(0, 1, At, B1); PG8_BAR;
;             PG8_LDA(At, 1, 1); PG8_STAGE(PG8_SA(1, 0), a3, voffA);
;             PG8_BAR; PG8_WAIT_L(0); PG8_MMA(1, 0, At, B0); PG8_BAR; PG8_SCHED;
;             PG8_STAGE(PG8_SB(1, 1), b3 + hstep, voffB);
;             PG8_WAIT_V(6); PG8_BAR; PG8_MMA(1, 1, At, B1); PG8_BAR;
;         }
	s_waitcnt lgkmcnt(0)
	s_waitcnt lgkmcnt(0)
	v_mfma_f32_16x16x32_bf16 v[122:125], v[196:199], v[164:167], v[122:125]
	v_mfma_f32_16x16x32_bf16 v[114:117], v[224:227], v[164:167], v[114:117]
	v_mfma_f32_16x16x32_bf16 v[106:109], v[196:199], v[172:175], v[106:109]
	v_mfma_f32_16x16x32_bf16 v[98:101], v[224:227], v[172:175], v[98:101]
	v_mfma_f32_16x16x32_bf16 v[90:93], v[196:199], v[180:183], v[90:93]
	v_mfma_f32_16x16x32_bf16 v[82:85], v[224:227], v[180:183], v[82:85]
	v_mfma_f32_16x16x32_bf16 v[74:77], v[196:199], v[188:191], v[74:77]
	v_mfma_f32_16x16x32_bf16 v[66:69], v[224:227], v[188:191], v[66:69]
	v_mfma_f32_16x16x32_bf16 v[122:125], v[200:203], v[168:171], v[122:125]
	v_mfma_f32_16x16x32_bf16 v[114:117], v[228:231], v[168:171], v[114:117]
	v_mfma_f32_16x16x32_bf16 v[106:109], v[200:203], v[176:179], v[106:109]
	v_mfma_f32_16x16x32_bf16 v[98:101], v[228:231], v[176:179], v[98:101]
	v_mfma_f32_16x16x32_bf16 v[90:93], v[200:203], v[184:187], v[90:93]
	v_mfma_f32_16x16x32_bf16 v[82:85], v[228:231], v[184:187], v[82:85]
	v_mfma_f32_16x16x32_bf16 v[74:77], v[200:203], v[192:195], v[74:77]
	v_mfma_f32_16x16x32_bf16 v[66:69], v[228:231], v[192:195], v[66:69]
	s_barrier
	v_add_u32 v146, s29, v1
	s_mov_b32 m0, s53
	v_add_u32_e32 v146, 0, v146
	ds_read_b128 v[164:167], v146 offset:49152
	ds_read_b128 v[168:171], v146 offset:50176
	ds_read_b128 v[172:175], v146 offset:51200
	ds_read_b128 v[176:179], v146 offset:52224
	ds_read_b128 v[180:183], v146 offset:53248
	ds_read_b128 v[184:187], v146 offset:54272
	ds_read_b128 v[188:191], v146 offset:55296
	ds_read_b128 v[192:195], v146 offset:56320
	v_lshl_add_u64 v[146:147], v[150:151], 0, s[30:31]
	global_load_lds_dwordx4 v[146:147], off
	v_lshl_add_u64 v[146:147], v[152:153], 0, s[30:31]
	s_mov_b32 m0, s74
	s_nop 0
	global_load_lds_dwordx4 v[146:147], off
	s_barrier
	s_waitcnt lgkmcnt(0)
	s_waitcnt lgkmcnt(0)
	v_mfma_f32_16x16x32_bf16 v[62:65], v[138:141], v[164:167], v[62:65]
	v_mfma_f32_16x16x32_bf16 v[54:57], v[156:159], v[164:167], v[54:57]
	v_mfma_f32_16x16x32_bf16 v[46:49], v[138:141], v[172:175], v[46:49]
	v_mfma_f32_16x16x32_bf16 v[38:41], v[156:159], v[172:175], v[38:41]
	v_mfma_f32_16x16x32_bf16 v[30:33], v[138:141], v[180:183], v[30:33]
	v_mfma_f32_16x16x32_bf16 v[22:25], v[156:159], v[180:183], v[22:25]
	v_mfma_f32_16x16x32_bf16 v[14:17], v[138:141], v[188:191], v[14:17]
	v_mfma_f32_16x16x32_bf16 v[6:9], v[156:159], v[188:191], v[6:9]
	v_mfma_f32_16x16x32_bf16 v[62:65], v[142:145], v[168:171], v[62:65]
	v_mfma_f32_16x16x32_bf16 v[54:57], v[160:163], v[168:171], v[54:57]
	v_mfma_f32_16x16x32_bf16 v[46:49], v[142:145], v[176:179], v[46:49]
	v_mfma_f32_16x16x32_bf16 v[38:41], v[160:163], v[176:179], v[38:41]
	v_mfma_f32_16x16x32_bf16 v[30:33], v[142:145], v[184:187], v[30:33]
	v_mfma_f32_16x16x32_bf16 v[22:25], v[160:163], v[184:187], v[22:25]
	v_mfma_f32_16x16x32_bf16 v[14:17], v[142:145], v[192:195], v[14:17]
	v_mfma_f32_16x16x32_bf16 v[6:9], v[160:163], v[192:195], v[6:9]
	s_barrier
	s_add_u32 s2, s20, 0x18080
	s_addc_u32 s3, s21, 0
	s_add_i32 s18, s19, s10
	v_lshl_add_u64 v[138:139], s[2:3], 0, v[130:131]
	s_mov_b32 m0, s18
	s_nop 0
	global_load_lds_dwordx4 v[138:139], off
	v_lshl_add_u64 v[138:139], s[2:3], 0, v[132:133]
	s_add_i32 m0, s18, 0x2000
	s_nop 0
	global_load_lds_dwordx4 v[138:139], off
	s_waitcnt vmcnt(6)
	s_barrier
	v_mfma_f32_16x16x32_bf16 v[58:61], v[196:199], v[164:167], v[58:61]
	v_mfma_f32_16x16x32_bf16 v[50:53], v[224:227], v[164:167], v[50:53]
	v_mfma_f32_16x16x32_bf16 v[42:45], v[196:199], v[172:175], v[42:45]
	v_mfma_f32_16x16x32_bf16 v[34:37], v[224:227], v[172:175], v[34:37]
	v_mfma_f32_16x16x32_bf16 v[26:29], v[196:199], v[180:183], v[26:29]
	v_mfma_f32_16x16x32_bf16 v[18:21], v[224:227], v[180:183], v[18:21]
	v_mfma_f32_16x16x32_bf16 v[10:13], v[196:199], v[188:191], v[10:13]
	v_mfma_f32_16x16x32_bf16 v[2:5], v[224:227], v[188:191], v[2:5]
	v_mfma_f32_16x16x32_bf16 v[58:61], v[200:203], v[168:171], v[58:61]
	v_mfma_f32_16x16x32_bf16 v[50:53], v[228:231], v[168:171], v[50:53]
	v_mfma_f32_16x16x32_bf16 v[42:45], v[200:203], v[176:179], v[42:45]
	v_mfma_f32_16x16x32_bf16 v[34:37], v[228:231], v[176:179], v[34:37]
	v_mfma_f32_16x16x32_bf16 v[26:29], v[200:203], v[184:187], v[26:29]
	v_mfma_f32_16x16x32_bf16 v[18:21], v[228:231], v[184:187], v[18:21]
	v_mfma_f32_16x16x32_bf16 v[10:13], v[200:203], v[192:195], v[10:13]
	v_mfma_f32_16x16x32_bf16 v[2:5], v[228:231], v[192:195], v[2:5]
	s_add_u32 s41, s41, 0x100
	s_addc_u32 s42, s42, 0
	s_cmp_ge_u32 s43, s5
	s_mov_b64 s[2:3], s[16:17]
	s_mov_b32 s20, s43
	s_barrier
	s_cbranch_scc0 .LBB0_658
	s_cmp_lt_i32 s60, 3
	s_cselect_b64 s[40:41], -1, 0
	s_cmp_gt_i32 s60, 2
	s_cselect_b64 s[16:17], -1, 0
	s_and_b64 s[50:51], s[24:25], s[16:17]
	v_readlane_b32 s2, v255, 13
	v_mov_b32_e32 v140, v253
	s_movk_i32 s26, 0x180
	s_and_b64 vcc, exec, s[50:51]
	v_readlane_b32 s3, v255, 14
	s_cbranch_vccnz .LBB0_665
	s_mov_b64 s[20:21], -1
	s_and_b64 vcc, exec, s[16:17]
	s_cbranch_vccz .LBB0_662
	s_load_dwordx2 s[2:3], s[0:1], 0x88
	v_readlane_b32 s16, v255, 49
	v_readlane_b32 s17, v255, 50
	s_lshl_b64 s[16:17], s[16:17], 2
	s_mov_b64 s[20:21], 0
	s_waitcnt lgkmcnt(0)
	s_add_u32 s2, s2, s16
	s_addc_u32 s3, s3, s17

; #define PG8_STAGE(bufoff, gbase, voff) do { _Pragma("unroll") for (int _i = 0; _i < 2; ++_i) \
;         __builtin_amdgcn_global_load_lds((const unsigned*)((const char*)(gbase) + (voff)[_i]), (PG8_LAS unsigned*)(lds + (bufoff) + ldsw + _i * 8192), 16, 0, 0); } while (0)
; #define PG8_LDA(dst, b, h) do { int aoff; asm volatile("v_add_u32 %0, %1, %2" : "=v"(aoff) : "s"(ua), "v"(foff)); _Pragma("unroll") for (int m = 0; m < 4; ++m) _Pragma("unroll") for (int k = 0; k < 2; ++k) dst[m][k] = *(const PG8_LAS bf16x8*)(lds + PG8_SA(b, h) + aoff + m * 2048 + k * 1024); } while (0)
; #define PG8_LDB(dst, b, h) do { int boff; asm volatile("v_add_u32 %0, %1, %2" : "=v"(boff) : "s"(ub), "v"(foff)); _Pragma("unroll") for (int n = 0; n < 2; ++n) _Pragma("unroll") for (int k = 0; k < 2; ++k) dst[n][k] = *(const PG8_LAS bf16x8*)(lds + PG8_SB(b, h) + boff + n * 2048 + k * 1024); } while (0)
; #define PG8_MMA(ai, bj, At, Bt) do { __builtin_amdgcn_s_setprio(1); _Pragma("unroll") for (int m = 0; m < 4; ++m) _Pragma("unroll") for (int n = 0; n < 2; ++n) _Pragma("unroll") for (int k = 0; k < 2; ++k) \
;         acc[ai][bj][m][n] = __builtin_amdgcn_mfma_f32_16x16x32_bf16(Bt[n][k], At[m][k], acc[ai][bj][m][n], 0, 0, 0); __builtin_amdgcn_s_setprio(0); } while (0)
; #define PG8_WAIT_L(n) asm volatile("s_waitcnt lgkmcnt(" #n ")" ::: "memory")
; #define PG8_BAR __builtin_amdgcn_s_barrier()
; template <class Epi, class Sched>
; __device__ __forceinline__ void gemm_phase(PG8_LAS unsigned char* lds, const Gemm g, const Sched& S, const Epi& E) {
;     ...
;             const bool last = (t == cnt - 2);
;             const char* a1 = cA + (size_t)(t + 1) * kstep;
;             const char* a2 = last ? nA : cA + (size_t)(t + 2) * kstep; const char* b2 = last ? nB : cB + (size_t)(t + 2) * kstep;
;             const char* a3 = a2 + kstep; const char* b3 = b2 + kstep;
;             if (last && has_next) S.a_ready(nxt);
;             PG8_LDB(B0, 0, 0); PG8_SCHED; PG8_LDA(At, 0, 0); PG8_STAGE(PG8_SA(1, 1), a1 + hstep, voffA);
;             PG8_WAIT_L(8); PG8_BAR; PG8_WAIT_L(0); PG8_MMA(0, 0, At, B0); PG8_BAR; PG8_SCHED;
;             PG8_LDB(B1, 0, 1); PG8_STAGE(PG8_SB(0, 0), b2, voffB);
;             PG8_BAR; PG8_WAIT_L(0); PG8_MMA(0, 1, At, B1); PG8_BAR;
;             PG8_LDA(At, 0, 1); PG8_STAGE(PG8_SA(0, 0), a2, voffA);
;             PG8_BAR; PG8_WAIT_L(0); PG8_MMA(1, 0, At, B0); PG8_BAR; PG8_SCHED;
.LBB0_975:
	s_add_i32 s54, s26, 2
	s_add_u32 s16, s2, 0x100
	s_addc_u32 s17, s3, 0
	s_add_i32 s18, 0, 0x10000
	v_add_u32 v130, s61, v1
	s_cmp_eq_u32 s5, s26
	v_add_u32_e32 v142, s18, v130
	ds_read_b128 v[130:133], v142
	ds_read_b128 v[134:137], v142 offset:1024
	ds_read_b128 v[138:141], v142 offset:2048
	ds_read_b128 v[142:145], v142 offset:3072
	s_cselect_b32 s26, s38, s25
	s_cselect_b32 s29, s49, s17
	s_cselect_b32 s28, s48, s16
	s_cselect_b32 s27, s39, s45
	v_add_u32 v146, s60, v1
	v_lshl_add_u64 v[194:195], s[2:3], 0, v[164:165]
	v_add_u32_e32 v169, 0, v146
	s_add_i32 m0, s12, 0xc000
	ds_read_b128 v[146:149], v169
	ds_read_b128 v[150:153], v169 offset:1024
	ds_read_b128 v[170:173], v169 offset:2048
	ds_read_b128 v[174:177], v169 offset:3072
	ds_read_b128 v[178:181], v169 offset:4096
	ds_read_b128 v[182:185], v169 offset:5120
	ds_read_b128 v[186:189], v169 offset:6144
	ds_read_b128 v[190:193], v169 offset:7168
	global_load_lds_dwordx4 v[194:195], off
	v_lshl_add_u64 v[194:195], s[2:3], 0, v[166:167]
	s_add_i32 m0, s12, 0xe000
	s_nop 0
	global_load_lds_dwordx4 v[194:195], off
	s_waitcnt lgkmcnt(8)
	s_barrier
	s_waitcnt lgkmcnt(0)
	s_waitcnt lgkmcnt(0)
	v_mfma_f32_16x16x32_bf16 v[126:129], v[130:133], v[146:149], v[126:129]
	v_mfma_f32_16x16x32_bf16 v[122:125], v[138:141], v[146:149], v[122:125]
	v_mfma_f32_16x16x32_bf16 v[118:121], v[130:133], v[170:173], v[118:121]
	v_mfma_f32_16x16x32_bf16 v[114:117], v[138:141], v[170:173], v[114:117]
	v_mfma_f32_16x16x32_bf16 v[106:109], v[130:133], v[178:181], v[106:109]
	v_mfma_f32_16x16x32_bf16 v[98:101], v[138:141], v[178:181], v[98:101]
	v_mfma_f32_16x16x32_bf16 v[90:93], v[130:133], v[186:189], v[90:93]
	v_mfma_f32_16x16x32_bf16 v[82:85], v[138:141], v[186:189], v[82:85]
	v_mfma_f32_16x16x32_bf16 v[126:129], v[134:137], v[150:153], v[126:129]
	v_mfma_f32_16x16x32_bf16 v[122:125], v[142:145], v[150:153], v[122:125]
	v_mfma_f32_16x16x32_bf16 v[118:121], v[134:137], v[174:177], v[118:121]
	v_mfma_f32_16x16x32_bf16 v[114:117], v[142:145], v[174:177], v[114:117]
	v_mfma_f32_16x16x32_bf16 v[106:109], v[134:137], v[182:185], v[106:109]
	v_mfma_f32_16x16x32_bf16 v[98:101], v[142:145], v[182:185], v[98:101]
	v_mfma_f32_16x16x32_bf16 v[90:93], v[134:137], v[190:193], v[90:93]
	v_mfma_f32_16x16x32_bf16 v[82:85], v[142:145], v[190:193], v[82:85]
	s_barrier
	v_add_u32 v169, s61, v1
	s_add_i32 s19, 0, 0x14000
	s_add_i32 s2, s18, s10
	v_add_u32_e32 v169, s19, v169
	v_lshl_add_u64 v[212:213], s[26:27], 0, v[156:157]
	s_mov_b32 m0, s2
	ds_read_b128 v[194:197], v169
	ds_read_b128 v[198:201], v169 offset:1024
	ds_read_b128 v[202:205], v169 offset:2048
	ds_read_b128 v[206:209], v169 offset:3072
	global_load_lds_dwordx4 v[212:213], off
	v_lshl_add_u64 v[214:215], s[26:27], 0, v[158:159]
	s_add_i32 m0, s2, 0x2000
	s_nop 0
	global_load_lds_dwordx4 v[214:215], off
	s_barrier
	s_waitcnt lgkmcnt(0)
	s_waitcnt lgkmcnt(0)
	v_mfma_f32_16x16x32_bf16 v[110:113], v[194:197], v[146:149], v[110:113]
	v_mfma_f32_16x16x32_bf16 v[102:105], v[202:205], v[146:149], v[102:105]
	v_mfma_f32_16x16x32_bf16 v[94:97], v[194:197], v[170:173], v[94:97]
	v_mfma_f32_16x16x32_bf16 v[86:89], v[202:205], v[170:173], v[86:89]
	v_mfma_f32_16x16x32_bf16 v[78:81], v[194:197], v[178:181], v[78:81]
	v_mfma_f32_16x16x32_bf16 v[74:77], v[202:205], v[178:181], v[74:77]
	v_mfma_f32_16x16x32_bf16 v[70:73], v[194:197], v[186:189], v[70:73]
	v_mfma_f32_16x16x32_bf16 v[66:69], v[202:205], v[186:189], v[66:69]
	v_mfma_f32_16x16x32_bf16 v[110:113], v[198:201], v[150:153], v[110:113]
	v_mfma_f32_16x16x32_bf16 v[102:105], v[206:209], v[150:153], v[102:105]
	v_mfma_f32_16x16x32_bf16 v[94:97], v[198:201], v[174:177], v[94:97]
	v_mfma_f32_16x16x32_bf16 v[86:89], v[206:209], v[174:177], v[86:89]
	v_mfma_f32_16x16x32_bf16 v[78:81], v[198:201], v[182:185], v[78:81]
	v_mfma_f32_16x16x32_bf16 v[74:77], v[206:209], v[182:185], v[74:77]
	v_mfma_f32_16x16x32_bf16 v[70:73], v[198:201], v[190:193], v[70:73]
	v_mfma_f32_16x16x32_bf16 v[66:69], v[206:209], v[190:193], v[66:69]
	s_mov_b32 m0, s12
	s_barrier
	v_add_u32 v146, s60, v1
	v_lshl_add_u64 v[218:219], s[28:29], 0, v[156:157]
	v_add_u32_e32 v169, 0, v146
	ds_read_b128 v[146:149], v169 offset:16384
	ds_read_b128 v[150:153], v169 offset:17408
	ds_read_b128 v[170:173], v169 offset:18432
	ds_read_b128 v[174:177], v169 offset:19456
	ds_read_b128 v[178:181], v169 offset:20480
	ds_read_b128 v[182:185], v169 offset:21504
	ds_read_b128 v[186:189], v169 offset:22528
	ds_read_b128 v[190:193], v169 offset:23552
	global_load_lds_dwordx4 v[218:219], off
	v_lshl_add_u64 v[220:221], s[28:29], 0, v[158:159]
	s_mov_b32 m0, s13
	s_nop 0
	global_load_lds_dwordx4 v[220:221], off
	s_barrier
	s_waitcnt lgkmcnt(0)
	s_waitcnt lgkmcnt(0)
	v_mfma_f32_16x16x32_bf16 v[62:65], v[130:133], v[146:149], v[62:65]
	v_mfma_f32_16x16x32_bf16 v[58:61], v[138:141], v[146:149], v[58:61]
	v_mfma_f32_16x16x32_bf16 v[54:57], v[130:133], v[170:173], v[54:57]
	v_mfma_f32_16x16x32_bf16 v[50:53], v[138:141], v[170:173], v[50:53]
	v_mfma_f32_16x16x32_bf16 v[38:41], v[130:133], v[178:181], v[38:41]
	v_mfma_f32_16x16x32_bf16 v[34:37], v[138:141], v[178:181], v[34:37]
	v_mfma_f32_16x16x32_bf16 v[22:25], v[130:133], v[186:189], v[22:25]
	v_mfma_f32_16x16x32_bf16 v[18:21], v[138:141], v[186:189], v[18:21]
	v_mfma_f32_16x16x32_bf16 v[62:65], v[134:137], v[150:153], v[62:65]
	v_mfma_f32_16x16x32_bf16 v[58:61], v[142:145], v[150:153], v[58:61]
	v_mfma_f32_16x16x32_bf16 v[54:57], v[134:137], v[174:177], v[54:57]
	v_mfma_f32_16x16x32_bf16 v[50:53], v[142:145], v[174:177], v[50:53]
	v_mfma_f32_16x16x32_bf16 v[38:41], v[134:137], v[182:185], v[38:41]
	v_mfma_f32_16x16x32_bf16 v[34:37], v[142:145], v[182:185], v[34:37]
	v_mfma_f32_16x16x32_bf16 v[22:25], v[134:137], v[190:193], v[22:25]
	v_mfma_f32_16x16x32_bf16 v[18:21], v[142:145], v[190:193], v[18:21]
	s_barrier
; #define PG8_STAGE(bufoff, gbase, voff) do { _Pragma("unroll") for (int _i = 0; _i < 2; ++_i) \
;         __builtin_amdgcn_global_load_lds((const unsigned*)((const char*)(gbase) + (voff)[_i]), (PG8_LAS unsigned*)(lds + (bufoff) + ldsw + _i * 8192), 16, 0, 0); } while (0)
; #define PG8_LDA(dst, b, h) do { int aoff; asm volatile("v_add_u32 %0, %1, %2" : "=v"(aoff) : "s"(ua), "v"(foff)); _Pragma("unroll") for (int m = 0; m < 4; ++m) _Pragma("unroll") for (int k = 0; k < 2; ++k) dst[m][k] = *(const PG8_LAS bf16x8*)(lds + PG8_SA(b, h) + aoff + m * 2048 + k * 1024); } while (0)
; #define PG8_LDB(dst, b, h) do { int boff; asm volatile("v_add_u32 %0, %1, %2" : "=v"(boff) : "s"(ub), "v"(foff)); _Pragma("unroll") for (int n = 0; n < 2; ++n) _Pragma("unroll") for (int k = 0; k < 2; ++k) dst[n][k] = *(const PG8_LAS bf16x8*)(lds + PG8_SB(b, h) + boff + n * 2048 + k * 1024); } while (0)
; #define PG8_MMA(ai, bj, At, Bt) do { __builtin_amdgcn_s_setprio(1); _Pragma("unroll") for (int m = 0; m < 4; ++m) _Pragma("unroll") for (int n = 0; n < 2; ++n) _Pragma("unroll") for (int k = 0; k < 2; ++k) \
;         acc[ai][bj][m][n] = __builtin_amdgcn_mfma_f32_16x16x32_bf16(Bt[n][k], At[m][k], acc[ai][bj][m][n], 0, 0, 0); __builtin_amdgcn_s_setprio(0); } while (0)
; #define PG8_WAIT_V(n) asm volatile("s_waitcnt vmcnt(" #n ")" ::: "memory")
; #define PG8_WAIT_L(n) asm volatile("s_waitcnt lgkmcnt(" #n ")" ::: "memory")
; #define PG8_BAR __builtin_amdgcn_s_barrier()
; #define PG8_SCHED __builtin_amdgcn_sched_barrier(0)
; template <class Epi, class Sched>
; __device__ __forceinline__ void gemm_phase(PG8_LAS unsigned char* lds, const Gemm g, const Sched& S, const Epi& E) {
;     ...
;             PG8_STAGE(PG8_SB(0, 1), b2 + hstep, voffB);
;             PG8_WAIT_V(6); PG8_BAR; PG8_MMA(1, 1, At, B1); PG8_BAR;
;             PG8_LDB(B0, 1, 0); PG8_SCHED; PG8_LDA(At, 1, 0); PG8_STAGE(PG8_SA(0, 1), a2 + hstep, voffA);
;             PG8_WAIT_L(8); PG8_BAR; PG8_WAIT_L(0); PG8_MMA(0, 0, At, B0); PG8_BAR; PG8_SCHED;
;             PG8_LDB(B1, 1, 1); PG8_STAGE(PG8_SB(1, 0), b3, voffB);
	s_add_u32 s2, s26, 0x50000
	s_addc_u32 s3, s27, 0
	s_add_i32 s18, s19, s10
	v_lshl_add_u64 v[130:131], s[2:3], 0, v[156:157]
	s_mov_b32 m0, s18
	s_nop 0
	global_load_lds_dwordx4 v[130:131], off
	v_lshl_add_u64 v[130:131], s[2:3], 0, v[158:159]
	s_add_i32 m0, s18, 0x2000
	s_nop 0
	global_load_lds_dwordx4 v[130:131], off
	s_waitcnt vmcnt(6)
	s_barrier
	v_mfma_f32_16x16x32_bf16 v[46:49], v[194:197], v[146:149], v[46:49]
	v_mfma_f32_16x16x32_bf16 v[42:45], v[202:205], v[146:149], v[42:45]
	v_mfma_f32_16x16x32_bf16 v[30:33], v[194:197], v[170:173], v[30:33]
	v_mfma_f32_16x16x32_bf16 v[26:29], v[202:205], v[170:173], v[26:29]
	v_mfma_f32_16x16x32_bf16 v[14:17], v[194:197], v[178:181], v[14:17]
	v_mfma_f32_16x16x32_bf16 v[10:13], v[202:205], v[178:181], v[10:13]
	v_mfma_f32_16x16x32_bf16 v[6:9], v[194:197], v[186:189], v[6:9]
	v_mfma_f32_16x16x32_bf16 v[2:5], v[202:205], v[186:189], v[2:5]
	v_mfma_f32_16x16x32_bf16 v[46:49], v[198:201], v[150:153], v[46:49]
	v_mfma_f32_16x16x32_bf16 v[42:45], v[206:209], v[150:153], v[42:45]
	v_mfma_f32_16x16x32_bf16 v[30:33], v[198:201], v[174:177], v[30:33]
	v_mfma_f32_16x16x32_bf16 v[26:29], v[206:209], v[174:177], v[26:29]
	v_mfma_f32_16x16x32_bf16 v[14:17], v[198:201], v[182:185], v[14:17]
	v_mfma_f32_16x16x32_bf16 v[10:13], v[206:209], v[182:185], v[10:13]
	v_mfma_f32_16x16x32_bf16 v[6:9], v[198:201], v[190:193], v[6:9]
	v_mfma_f32_16x16x32_bf16 v[2:5], v[206:209], v[190:193], v[2:5]
	s_add_i32 s18, 0, 0x18000
	s_barrier
	v_add_u32 v130, s61, v1
	s_nop 0
	v_add_u32_e32 v142, s18, v130
	ds_read_b128 v[130:133], v142
	ds_read_b128 v[134:137], v142 offset:1024
	ds_read_b128 v[138:141], v142 offset:2048
	ds_read_b128 v[142:145], v142 offset:3072
	s_add_u32 s2, s28, 0x50000
	s_addc_u32 s3, s29, 0
	s_mov_b32 m0, s50
	v_add_u32 v146, s60, v1
	v_lshl_add_u64 v[194:195], s[2:3], 0, v[156:157]
	v_add_u32_e32 v169, 0, v146
	ds_read_b128 v[146:149], v169 offset:32768
	ds_read_b128 v[150:153], v169 offset:33792
	ds_read_b128 v[170:173], v169 offset:34816
	ds_read_b128 v[174:177], v169 offset:35840
	ds_read_b128 v[178:181], v169 offset:36864
	ds_read_b128 v[182:185], v169 offset:37888
	ds_read_b128 v[186:189], v169 offset:38912
	ds_read_b128 v[190:193], v169 offset:39936
	global_load_lds_dwordx4 v[194:195], off
	v_lshl_add_u64 v[194:195], s[2:3], 0, v[158:159]
	s_mov_b32 m0, s51
	s_nop 0
	global_load_lds_dwordx4 v[194:195], off
	s_waitcnt lgkmcnt(8)
	s_barrier
	s_waitcnt lgkmcnt(0)
	s_waitcnt lgkmcnt(0)
	v_mfma_f32_16x16x32_bf16 v[126:129], v[130:133], v[146:149], v[126:129]
	v_mfma_f32_16x16x32_bf16 v[122:125], v[138:141], v[146:149], v[122:125]
	v_mfma_f32_16x16x32_bf16 v[118:121], v[130:133], v[170:173], v[118:121]
	v_mfma_f32_16x16x32_bf16 v[114:117], v[138:141], v[170:173], v[114:117]
	v_mfma_f32_16x16x32_bf16 v[106:109], v[130:133], v[178:181], v[106:109]
	v_mfma_f32_16x16x32_bf16 v[98:101], v[138:141], v[178:181], v[98:101]
	v_mfma_f32_16x16x32_bf16 v[90:93], v[130:133], v[186:189], v[90:93]
	v_mfma_f32_16x16x32_bf16 v[82:85], v[138:141], v[186:189], v[82:85]
	v_mfma_f32_16x16x32_bf16 v[126:129], v[134:137], v[150:153], v[126:129]
	v_mfma_f32_16x16x32_bf16 v[122:125], v[142:145], v[150:153], v[122:125]
	v_mfma_f32_16x16x32_bf16 v[118:121], v[134:137], v[174:177], v[118:121]
	v_mfma_f32_16x16x32_bf16 v[114:117], v[142:145], v[174:177], v[114:117]
	v_mfma_f32_16x16x32_bf16 v[106:109], v[134:137], v[182:185], v[106:109]
	v_mfma_f32_16x16x32_bf16 v[98:101], v[142:145], v[182:185], v[98:101]
	v_mfma_f32_16x16x32_bf16 v[90:93], v[134:137], v[190:193], v[90:93]
	v_mfma_f32_16x16x32_bf16 v[82:85], v[142:145], v[190:193], v[82:85]
	s_barrier
	v_add_u32 v169, s61, v1
	s_add_i32 s19, 0, 0x1c000
	s_add_i32 s2, s18, s10
	v_add_u32_e32 v169, s19, v169
	v_lshl_add_u64 v[212:213], v[212:213], 0, s[30:31]
	s_mov_b32 m0, s2
	ds_read_b128 v[194:197], v169
	ds_read_b128 v[198:201], v169 offset:1024
	ds_read_b128 v[202:205], v169 offset:2048
	ds_read_b128 v[206:209], v169 offset:3072
	global_load_lds_dwordx4 v[212:213], off
	v_lshl_add_u64 v[212:213], v[214:215], 0, s[30:31]
	s_add_i32 m0, s2, 0x2000
	s_nop 0
	global_load_lds_dwordx4 v[212:213], off
	s_barrier
; #define PG8_STAGE(bufoff, gbase, voff) do { _Pragma("unroll") for (int _i = 0; _i < 2; ++_i) \
;         __builtin_amdgcn_global_load_lds((const unsigned*)((const char*)(gbase) + (voff)[_i]), (PG8_LAS unsigned*)(lds + (bufoff) + ldsw + _i * 8192), 16, 0, 0); } while (0)
; #define PG8_LDA(dst, b, h) do { int aoff; asm volatile("v_add_u32 %0, %1, %2" : "=v"(aoff) : "s"(ua), "v"(foff)); _Pragma("unroll") for (int m = 0; m < 4; ++m) _Pragma("unroll") for (int k = 0; k < 2; ++k) dst[m][k] = *(const PG8_LAS bf16x8*)(lds + PG8_SA(b, h) + aoff + m * 2048 + k * 1024); } while (0)
; #define PG8_WAIT_V(n) asm volatile("s_waitcnt vmcnt(" #n ")" ::: "memory")
; #define PG8_WAIT_L(n) asm volatile("s_waitcnt lgkmcnt(" #n ")" ::: "memory")
; #define PG8_BAR __builtin_amdgcn_s_barrier()
; #define PG8_SCHED __builtin_amdgcn_sched_barrier(0)
;     __device__ __forceinline__ void operator()(const f32x4 (&acc)[2][2][4][2], const Unit& u, int wr, int wc, int fr, int fq) const {
;         if (u.kh >= 0) {
;             float* pb = part + ((size_t)u.kh * 4096 + (size_t)(u.pm - 128) * BM + wr * 64 + fr) * 1024 + u.pn * BM + wc * 32 + 4 * fq;
; #pragma unroll
;             for (int ai = 0; ai < 2; ++ai)
; #pragma unroll
;                 for (int m = 0; m < 4; ++m)
; #pragma unroll
;                     for (int bj = 0; bj < 2; ++bj)
; #pragma unroll
;                         for (int n = 0; n < 2; ++n) *(f32x4*)(pb + (size_t)(ai * HALF + m * 16) * 1024 + bj * HALF + n * 16) = acc[ai][bj][m][n];
;             return;
;         }
;         const bool isctx = u.pm >= 128;
;         const float* inb = isctx ? in_ctx : in_lat; float* outb = isctx ? out_ctx : out_lat;
;         const int pml = isctx ? u.pm - 128 : u.pm;
;         const float* gp = gate + (size_t)(isctx ? 16 : (u.pm >> 3)) * 6144;
; template <class Epi, class Sched>
; __device__ __forceinline__ void gemm_phase(PG8_LAS unsigned char* lds, const Gemm g, const Sched& S, const Epi& E) {
;     ...
;             PG8_BAR; PG8_WAIT_L(0); PG8_MMA(0, 1, At, B1); PG8_BAR;
;             PG8_LDA(At, 1, 1); PG8_STAGE(PG8_SA(1, 0), a3, voffA);
;             PG8_BAR; PG8_WAIT_L(0); PG8_MMA(1, 0, At, B0); PG8_BAR; PG8_SCHED;
;             PG8_STAGE(PG8_SB(1, 1), b3 + hstep, voffB);
;             PG8_WAIT_V(6); PG8_BAR; PG8_MMA(1, 1, At, B1); PG8_BAR;
;         }
	s_waitcnt lgkmcnt(0)
	s_waitcnt lgkmcnt(0)
	v_mfma_f32_16x16x32_bf16 v[110:113], v[194:197], v[146:149], v[110:113]
	v_mfma_f32_16x16x32_bf16 v[102:105], v[202:205], v[146:149], v[102:105]
	v_mfma_f32_16x16x32_bf16 v[94:97], v[194:197], v[170:173], v[94:97]
	v_mfma_f32_16x16x32_bf16 v[86:89], v[202:205], v[170:173], v[86:89]
	v_mfma_f32_16x16x32_bf16 v[78:81], v[194:197], v[178:181], v[78:81]
	v_mfma_f32_16x16x32_bf16 v[74:77], v[202:205], v[178:181], v[74:77]
	v_mfma_f32_16x16x32_bf16 v[70:73], v[194:197], v[186:189], v[70:73]
	v_mfma_f32_16x16x32_bf16 v[66:69], v[202:205], v[186:189], v[66:69]
	v_mfma_f32_16x16x32_bf16 v[110:113], v[198:201], v[150:153], v[110:113]
	v_mfma_f32_16x16x32_bf16 v[102:105], v[206:209], v[150:153], v[102:105]
	v_mfma_f32_16x16x32_bf16 v[94:97], v[198:201], v[174:177], v[94:97]
	v_mfma_f32_16x16x32_bf16 v[86:89], v[206:209], v[174:177], v[86:89]
	v_mfma_f32_16x16x32_bf16 v[78:81], v[198:201], v[182:185], v[78:81]
	v_mfma_f32_16x16x32_bf16 v[74:77], v[206:209], v[182:185], v[74:77]
	v_mfma_f32_16x16x32_bf16 v[70:73], v[198:201], v[190:193], v[70:73]
	v_mfma_f32_16x16x32_bf16 v[66:69], v[206:209], v[190:193], v[66:69]
	s_mov_b32 m0, s62
	s_barrier
	v_add_u32 v146, s60, v1
	v_lshl_add_u64 v[212:213], v[218:219], 0, s[30:31]
	v_add_u32_e32 v169, 0, v146
	ds_read_b128 v[146:149], v169 offset:49152
	ds_read_b128 v[150:153], v169 offset:50176
	ds_read_b128 v[170:173], v169 offset:51200
	ds_read_b128 v[174:177], v169 offset:52224
	ds_read_b128 v[178:181], v169 offset:53248
	ds_read_b128 v[182:185], v169 offset:54272
	ds_read_b128 v[186:189], v169 offset:55296
	ds_read_b128 v[190:193], v169 offset:56320
	global_load_lds_dwordx4 v[212:213], off
	v_lshl_add_u64 v[212:213], v[220:221], 0, s[30:31]
	s_mov_b32 m0, s63
	s_nop 0
	global_load_lds_dwordx4 v[212:213], off
	s_barrier
	s_waitcnt lgkmcnt(0)
	s_waitcnt lgkmcnt(0)
	v_mfma_f32_16x16x32_bf16 v[62:65], v[130:133], v[146:149], v[62:65]
	v_mfma_f32_16x16x32_bf16 v[58:61], v[138:141], v[146:149], v[58:61]
	v_mfma_f32_16x16x32_bf16 v[54:57], v[130:133], v[170:173], v[54:57]
	v_mfma_f32_16x16x32_bf16 v[50:53], v[138:141], v[170:173], v[50:53]
	v_mfma_f32_16x16x32_bf16 v[38:41], v[130:133], v[178:181], v[38:41]
	v_mfma_f32_16x16x32_bf16 v[34:37], v[138:141], v[178:181], v[34:37]
	v_mfma_f32_16x16x32_bf16 v[22:25], v[130:133], v[186:189], v[22:25]
	v_mfma_f32_16x16x32_bf16 v[18:21], v[138:141], v[186:189], v[18:21]
	v_mfma_f32_16x16x32_bf16 v[62:65], v[134:137], v[150:153], v[62:65]
	v_mfma_f32_16x16x32_bf16 v[58:61], v[142:145], v[150:153], v[58:61]
	v_mfma_f32_16x16x32_bf16 v[54:57], v[134:137], v[174:177], v[54:57]
	v_mfma_f32_16x16x32_bf16 v[50:53], v[142:145], v[174:177], v[50:53]
	v_mfma_f32_16x16x32_bf16 v[38:41], v[134:137], v[182:185], v[38:41]
	v_mfma_f32_16x16x32_bf16 v[34:37], v[142:145], v[182:185], v[34:37]
	v_mfma_f32_16x16x32_bf16 v[22:25], v[134:137], v[190:193], v[22:25]
	v_mfma_f32_16x16x32_bf16 v[18:21], v[142:145], v[190:193], v[18:21]
	s_barrier
	s_add_u32 s2, s26, 0x50080
	s_addc_u32 s3, s27, 0
	s_add_i32 s18, s19, s10
	v_lshl_add_u64 v[130:131], s[2:3], 0, v[156:157]
	s_mov_b32 m0, s18
	s_nop 0
	global_load_lds_dwordx4 v[130:131], off
	v_lshl_add_u64 v[130:131], s[2:3], 0, v[158:159]
	s_add_i32 m0, s18, 0x2000
	s_nop 0
	global_load_lds_dwordx4 v[130:131], off
	s_waitcnt vmcnt(6)
	s_barrier
	v_mfma_f32_16x16x32_bf16 v[46:49], v[194:197], v[146:149], v[46:49]
	v_mfma_f32_16x16x32_bf16 v[42:45], v[202:205], v[146:149], v[42:45]
	v_mfma_f32_16x16x32_bf16 v[30:33], v[194:197], v[170:173], v[30:33]
	v_mfma_f32_16x16x32_bf16 v[26:29], v[202:205], v[170:173], v[26:29]
	v_mfma_f32_16x16x32_bf16 v[14:17], v[194:197], v[178:181], v[14:17]
	v_mfma_f32_16x16x32_bf16 v[10:13], v[202:205], v[178:181], v[10:13]
	v_mfma_f32_16x16x32_bf16 v[6:9], v[194:197], v[186:189], v[6:9]
	v_mfma_f32_16x16x32_bf16 v[2:5], v[202:205], v[186:189], v[2:5]
	v_mfma_f32_16x16x32_bf16 v[46:49], v[198:201], v[150:153], v[46:49]
	v_mfma_f32_16x16x32_bf16 v[42:45], v[206:209], v[150:153], v[42:45]
	v_mfma_f32_16x16x32_bf16 v[30:33], v[198:201], v[174:177], v[30:33]
	v_mfma_f32_16x16x32_bf16 v[26:29], v[206:209], v[174:177], v[26:29]
	v_mfma_f32_16x16x32_bf16 v[14:17], v[198:201], v[182:185], v[14:17]
	v_mfma_f32_16x16x32_bf16 v[10:13], v[206:209], v[182:185], v[10:13]
	v_mfma_f32_16x16x32_bf16 v[6:9], v[198:201], v[190:193], v[6:9]
	v_mfma_f32_16x16x32_bf16 v[2:5], v[206:209], v[190:193], v[2:5]
	s_add_u32 s25, s25, 0x100
	s_addc_u32 s45, s45, 0
	s_cmp_ge_u32 s54, s21
	s_mov_b64 s[2:3], s[16:17]
	s_mov_b32 s26, s54
	s_barrier
	s_cbranch_scc0 .LBB0_975
	s_cmp_lt_i32 s24, 0
	s_mov_b64 s[2:3], -1
	s_cbranch_scc0 .LBB0_980
	s_cmpk_gt_i32 s20, 0x7f
	s_cselect_b64 s[26:27], -1, 0
	s_mov_b64 s[28:29], 0x18000
	s_and_b64 vcc, exec, s[26:27]
	s_cbranch_vccnz .LBB0_979
	s_ashr_i32 s2, s20, 3
	s_mul_hi_i32 s29, s2, 0x1800
	s_mul_i32 s28, s2, 0x1800

; #define PG8_STAGE(bufoff, gbase, voff) do { _Pragma("unroll") for (int _i = 0; _i < 2; ++_i) \
;         __builtin_amdgcn_global_load_lds((const unsigned*)((const char*)(gbase) + (voff)[_i]), (PG8_LAS unsigned*)(lds + (bufoff) + ldsw + _i * 8192), 16, 0, 0); } while (0)
; #define PG8_LDA(dst, b, h) do { int aoff; asm volatile("v_add_u32 %0, %1, %2" : "=v"(aoff) : "s"(ua), "v"(foff)); _Pragma("unroll") for (int m = 0; m < 4; ++m) _Pragma("unroll") for (int k = 0; k < 2; ++k) dst[m][k] = *(const PG8_LAS bf16x8*)(lds + PG8_SA(b, h) + aoff + m * 2048 + k * 1024); } while (0)
; #define PG8_LDB(dst, b, h) do { int boff; asm volatile("v_add_u32 %0, %1, %2" : "=v"(boff) : "s"(ub), "v"(foff)); _Pragma("unroll") for (int n = 0; n < 2; ++n) _Pragma("unroll") for (int k = 0; k < 2; ++k) dst[n][k] = *(const PG8_LAS bf16x8*)(lds + PG8_SB(b, h) + boff + n * 2048 + k * 1024); } while (0)
; #define PG8_MMA(ai, bj, At, Bt) do { __builtin_amdgcn_s_setprio(1); _Pragma("unroll") for (int m = 0; m < 4; ++m) _Pragma("unroll") for (int n = 0; n < 2; ++n) _Pragma("unroll") for (int k = 0; k < 2; ++k) \
;         acc[ai][bj][m][n] = __builtin_amdgcn_mfma_f32_16x16x32_bf16(Bt[n][k], At[m][k], acc[ai][bj][m][n], 0, 0, 0); __builtin_amdgcn_s_setprio(0); } while (0)
; #define PG8_WAIT_L(n) asm volatile("s_waitcnt lgkmcnt(" #n ")" ::: "memory")
; #define PG8_BAR __builtin_amdgcn_s_barrier()
; template <class Epi, class Sched>
; __device__ __forceinline__ void gemm_phase(PG8_LAS unsigned char* lds, const Gemm g, const Sched& S, const Epi& E) {
;     ...
;             const bool last = (t == cnt - 2);
;             const char* a1 = cA + (size_t)(t + 1) * kstep;
;             const char* a2 = last ? nA : cA + (size_t)(t + 2) * kstep; const char* b2 = last ? nB : cB + (size_t)(t + 2) * kstep;
;             const char* a3 = a2 + kstep; const char* b3 = b2 + kstep;
;             if (last && has_next) S.a_ready(nxt);
;             PG8_LDB(B0, 0, 0); PG8_SCHED; PG8_LDA(At, 0, 0); PG8_STAGE(PG8_SA(1, 1), a1 + hstep, voffA);
;             PG8_WAIT_L(8); PG8_BAR; PG8_WAIT_L(0); PG8_MMA(0, 0, At, B0); PG8_BAR; PG8_SCHED;
;             PG8_LDB(B1, 0, 1); PG8_STAGE(PG8_SB(0, 0), b2, voffB);
;             PG8_BAR; PG8_WAIT_L(0); PG8_MMA(0, 1, At, B1); PG8_BAR;
;             PG8_LDA(At, 0, 1); PG8_STAGE(PG8_SA(0, 0), a2, voffA);
;             PG8_BAR; PG8_WAIT_L(0); PG8_MMA(1, 0, At, B0); PG8_BAR; PG8_SCHED;
.LBB0_1109:
	s_add_u32 s44, s26, 0xfffc0080
	s_addc_u32 s45, s27, -1
	s_add_i32 s75, 0, 0x10000
	v_add_u32 v142, s51, v1
	s_cmp_eq_u32 s74, 12
	v_add_u32_e32 v158, s75, v142
	ds_read_b128 v[142:145], v158
	ds_read_b128 v[146:149], v158 offset:1024
	ds_read_b128 v[150:153], v158 offset:2048
	ds_read_b128 v[158:161], v158 offset:3072
	s_cselect_b32 s47, s5, s45
	s_cselect_b32 s46, s21, s44
	s_cselect_b32 s45, s19, s63
	s_cselect_b32 s44, s61, s62
	v_add_u32 v162, s50, v1
	v_lshl_add_u64 v[194:195], s[26:27], 0, v[138:139]
	v_add_u32_e32 v190, 0, v162
	s_add_i32 m0, s3, 0xc000
	ds_read_b128 v[162:165], v190
	ds_read_b128 v[166:169], v190 offset:1024
	ds_read_b128 v[170:173], v190 offset:2048
	ds_read_b128 v[174:177], v190 offset:3072
	ds_read_b128 v[178:181], v190 offset:4096
	ds_read_b128 v[182:185], v190 offset:5120
	ds_read_b128 v[186:189], v190 offset:6144
	ds_read_b128 v[190:193], v190 offset:7168
	global_load_lds_dwordx4 v[194:195], off
	v_lshl_add_u64 v[194:195], s[26:27], 0, v[140:141]
	s_add_i32 m0, s3, 0xe000
	s_nop 0
	global_load_lds_dwordx4 v[194:195], off
	s_waitcnt lgkmcnt(8)
	s_barrier
	s_waitcnt lgkmcnt(0)
	s_waitcnt lgkmcnt(0)
	v_mfma_f32_16x16x32_bf16 v[126:129], v[142:145], v[162:165], v[126:129]
	v_mfma_f32_16x16x32_bf16 v[118:121], v[150:153], v[162:165], v[118:121]
	v_mfma_f32_16x16x32_bf16 v[110:113], v[142:145], v[170:173], v[110:113]
	v_mfma_f32_16x16x32_bf16 v[102:105], v[150:153], v[170:173], v[102:105]
	v_mfma_f32_16x16x32_bf16 v[94:97], v[142:145], v[178:181], v[94:97]
	v_mfma_f32_16x16x32_bf16 v[86:89], v[150:153], v[178:181], v[86:89]
	v_mfma_f32_16x16x32_bf16 v[78:81], v[142:145], v[186:189], v[78:81]
	v_mfma_f32_16x16x32_bf16 v[70:73], v[150:153], v[186:189], v[70:73]
	v_mfma_f32_16x16x32_bf16 v[126:129], v[146:149], v[166:169], v[126:129]
	v_mfma_f32_16x16x32_bf16 v[118:121], v[158:161], v[166:169], v[118:121]
	v_mfma_f32_16x16x32_bf16 v[110:113], v[146:149], v[174:177], v[110:113]
	v_mfma_f32_16x16x32_bf16 v[102:105], v[158:161], v[174:177], v[102:105]
	v_mfma_f32_16x16x32_bf16 v[94:97], v[146:149], v[182:185], v[94:97]
	v_mfma_f32_16x16x32_bf16 v[86:89], v[158:161], v[182:185], v[86:89]
	v_mfma_f32_16x16x32_bf16 v[78:81], v[146:149], v[190:193], v[78:81]
	v_mfma_f32_16x16x32_bf16 v[70:73], v[158:161], v[190:193], v[70:73]
	s_barrier
	s_add_i32 s78, 0, 0x14000
	s_add_i32 s75, s75, s11
	v_add_u32 v194, s51, v1
	v_lshl_add_u64 v[212:213], s[44:45], 0, v[134:135]
	v_add_u32_e32 v206, s78, v194
	s_mov_b32 m0, s75
	ds_read_b128 v[194:197], v206
	ds_read_b128 v[198:201], v206 offset:1024
	ds_read_b128 v[202:205], v206 offset:2048
	ds_read_b128 v[206:209], v206 offset:3072
	global_load_lds_dwordx4 v[212:213], off
	v_lshl_add_u64 v[214:215], s[44:45], 0, v[130:131]
	s_add_i32 m0, s75, 0x2000
	s_nop 0
	global_load_lds_dwordx4 v[214:215], off
	s_barrier
	s_waitcnt lgkmcnt(0)
	s_waitcnt lgkmcnt(0)
	v_mfma_f32_16x16x32_bf16 v[122:125], v[194:197], v[162:165], v[122:125]
	v_mfma_f32_16x16x32_bf16 v[114:117], v[202:205], v[162:165], v[114:117]
	v_mfma_f32_16x16x32_bf16 v[106:109], v[194:197], v[170:173], v[106:109]
	v_mfma_f32_16x16x32_bf16 v[98:101], v[202:205], v[170:173], v[98:101]
	v_mfma_f32_16x16x32_bf16 v[90:93], v[194:197], v[178:181], v[90:93]
	v_mfma_f32_16x16x32_bf16 v[82:85], v[202:205], v[178:181], v[82:85]
	v_mfma_f32_16x16x32_bf16 v[74:77], v[194:197], v[186:189], v[74:77]
	v_mfma_f32_16x16x32_bf16 v[66:69], v[202:205], v[186:189], v[66:69]
	v_mfma_f32_16x16x32_bf16 v[122:125], v[198:201], v[166:169], v[122:125]
	v_mfma_f32_16x16x32_bf16 v[114:117], v[206:209], v[166:169], v[114:117]
	v_mfma_f32_16x16x32_bf16 v[106:109], v[198:201], v[174:177], v[106:109]
	v_mfma_f32_16x16x32_bf16 v[98:101], v[206:209], v[174:177], v[98:101]
	v_mfma_f32_16x16x32_bf16 v[90:93], v[198:201], v[182:185], v[90:93]
	v_mfma_f32_16x16x32_bf16 v[82:85], v[206:209], v[182:185], v[82:85]
	v_mfma_f32_16x16x32_bf16 v[74:77], v[198:201], v[190:193], v[74:77]
	v_mfma_f32_16x16x32_bf16 v[66:69], v[206:209], v[190:193], v[66:69]
	s_mov_b32 m0, s3
	s_barrier
	v_add_u32 v162, s50, v1
	v_lshl_add_u64 v[218:219], s[46:47], 0, v[136:137]
	v_add_u32_e32 v190, 0, v162
	ds_read_b128 v[162:165], v190 offset:16384
	ds_read_b128 v[166:169], v190 offset:17408
	ds_read_b128 v[170:173], v190 offset:18432
	ds_read_b128 v[174:177], v190 offset:19456
	ds_read_b128 v[178:181], v190 offset:20480
	ds_read_b128 v[182:185], v190 offset:21504
	ds_read_b128 v[186:189], v190 offset:22528
	ds_read_b128 v[190:193], v190 offset:23552
	global_load_lds_dwordx4 v[218:219], off
	v_lshl_add_u64 v[220:221], s[46:47], 0, v[132:133]
	s_mov_b32 m0, s17
	s_nop 0
	global_load_lds_dwordx4 v[220:221], off
	s_barrier
	s_waitcnt lgkmcnt(0)
	s_waitcnt lgkmcnt(0)
	v_mfma_f32_16x16x32_bf16 v[62:65], v[142:145], v[162:165], v[62:65]
	v_mfma_f32_16x16x32_bf16 v[54:57], v[150:153], v[162:165], v[54:57]
	v_mfma_f32_16x16x32_bf16 v[46:49], v[142:145], v[170:173], v[46:49]
	v_mfma_f32_16x16x32_bf16 v[38:41], v[150:153], v[170:173], v[38:41]
	v_mfma_f32_16x16x32_bf16 v[30:33], v[142:145], v[178:181], v[30:33]
	v_mfma_f32_16x16x32_bf16 v[22:25], v[150:153], v[178:181], v[22:25]
	v_mfma_f32_16x16x32_bf16 v[14:17], v[142:145], v[186:189], v[14:17]
	v_mfma_f32_16x16x32_bf16 v[6:9], v[150:153], v[186:189], v[6:9]
	v_mfma_f32_16x16x32_bf16 v[62:65], v[146:149], v[166:169], v[62:65]
	v_mfma_f32_16x16x32_bf16 v[54:57], v[158:161], v[166:169], v[54:57]
	v_mfma_f32_16x16x32_bf16 v[46:49], v[146:149], v[174:177], v[46:49]
	v_mfma_f32_16x16x32_bf16 v[38:41], v[158:161], v[174:177], v[38:41]
	v_mfma_f32_16x16x32_bf16 v[30:33], v[146:149], v[182:185], v[30:33]
	v_mfma_f32_16x16x32_bf16 v[22:25], v[158:161], v[182:185], v[22:25]
	v_mfma_f32_16x16x32_bf16 v[14:17], v[146:149], v[190:193], v[14:17]
	v_mfma_f32_16x16x32_bf16 v[6:9], v[158:161], v[190:193], v[6:9]
	s_barrier
; #define PG8_STAGE(bufoff, gbase, voff) do { _Pragma("unroll") for (int _i = 0; _i < 2; ++_i) \
;         __builtin_amdgcn_global_load_lds((const unsigned*)((const char*)(gbase) + (voff)[_i]), (PG8_LAS unsigned*)(lds + (bufoff) + ldsw + _i * 8192), 16, 0, 0); } while (0)
; #define PG8_LDA(dst, b, h) do { int aoff; asm volatile("v_add_u32 %0, %1, %2" : "=v"(aoff) : "s"(ua), "v"(foff)); _Pragma("unroll") for (int m = 0; m < 4; ++m) _Pragma("unroll") for (int k = 0; k < 2; ++k) dst[m][k] = *(const PG8_LAS bf16x8*)(lds + PG8_SA(b, h) + aoff + m * 2048 + k * 1024); } while (0)
; #define PG8_LDB(dst, b, h) do { int boff; asm volatile("v_add_u32 %0, %1, %2" : "=v"(boff) : "s"(ub), "v"(foff)); _Pragma("unroll") for (int n = 0; n < 2; ++n) _Pragma("unroll") for (int k = 0; k < 2; ++k) dst[n][k] = *(const PG8_LAS bf16x8*)(lds + PG8_SB(b, h) + boff + n * 2048 + k * 1024); } while (0)
; #define PG8_MMA(ai, bj, At, Bt) do { __builtin_amdgcn_s_setprio(1); _Pragma("unroll") for (int m = 0; m < 4; ++m) _Pragma("unroll") for (int n = 0; n < 2; ++n) _Pragma("unroll") for (int k = 0; k < 2; ++k) \
;         acc[ai][bj][m][n] = __builtin_amdgcn_mfma_f32_16x16x32_bf16(Bt[n][k], At[m][k], acc[ai][bj][m][n], 0, 0, 0); __builtin_amdgcn_s_setprio(0); } while (0)
; #define PG8_WAIT_V(n) asm volatile("s_waitcnt vmcnt(" #n ")" ::: "memory")
; #define PG8_WAIT_L(n) asm volatile("s_waitcnt lgkmcnt(" #n ")" ::: "memory")
; #define PG8_BAR __builtin_amdgcn_s_barrier()
; #define PG8_SCHED __builtin_amdgcn_sched_barrier(0)
; template <class Epi, class Sched>
; __device__ __forceinline__ void gemm_phase(PG8_LAS unsigned char* lds, const Gemm g, const Sched& S, const Epi& E) {
;     ...
;             PG8_STAGE(PG8_SB(0, 1), b2 + hstep, voffB);
;             PG8_WAIT_V(6); PG8_BAR; PG8_MMA(1, 1, At, B1); PG8_BAR;
;             PG8_LDB(B0, 1, 0); PG8_SCHED; PG8_LDA(At, 1, 0); PG8_STAGE(PG8_SA(0, 1), a2 + hstep, voffA);
;             PG8_WAIT_L(8); PG8_BAR; PG8_WAIT_L(0); PG8_MMA(0, 0, At, B0); PG8_BAR; PG8_SCHED;
;             PG8_LDB(B1, 1, 1); PG8_STAGE(PG8_SB(1, 0), b3, voffB);
;             PG8_BAR; PG8_WAIT_L(0); PG8_MMA(0, 1, At, B1); PG8_BAR;
	s_add_u32 s76, s44, 0x40000
	s_addc_u32 s77, s45, 0
	s_add_i32 s75, s78, s11
	v_lshl_add_u64 v[142:143], s[76:77], 0, v[134:135]
	s_mov_b32 m0, s75
	s_nop 0
	global_load_lds_dwordx4 v[142:143], off
	v_lshl_add_u64 v[142:143], s[76:77], 0, v[130:131]
	s_add_i32 m0, s75, 0x2000
	s_nop 0
	global_load_lds_dwordx4 v[142:143], off
	s_waitcnt vmcnt(6)
	s_barrier
	v_mfma_f32_16x16x32_bf16 v[58:61], v[194:197], v[162:165], v[58:61]
	v_mfma_f32_16x16x32_bf16 v[50:53], v[202:205], v[162:165], v[50:53]
	v_mfma_f32_16x16x32_bf16 v[42:45], v[194:197], v[170:173], v[42:45]
	v_mfma_f32_16x16x32_bf16 v[34:37], v[202:205], v[170:173], v[34:37]
	v_mfma_f32_16x16x32_bf16 v[26:29], v[194:197], v[178:181], v[26:29]
	v_mfma_f32_16x16x32_bf16 v[18:21], v[202:205], v[178:181], v[18:21]
	v_mfma_f32_16x16x32_bf16 v[10:13], v[194:197], v[186:189], v[10:13]
	v_mfma_f32_16x16x32_bf16 v[2:5], v[202:205], v[186:189], v[2:5]
	v_mfma_f32_16x16x32_bf16 v[58:61], v[198:201], v[166:169], v[58:61]
	v_mfma_f32_16x16x32_bf16 v[50:53], v[206:209], v[166:169], v[50:53]
	v_mfma_f32_16x16x32_bf16 v[42:45], v[198:201], v[174:177], v[42:45]
	v_mfma_f32_16x16x32_bf16 v[34:37], v[206:209], v[174:177], v[34:37]
	v_mfma_f32_16x16x32_bf16 v[26:29], v[198:201], v[182:185], v[26:29]
	v_mfma_f32_16x16x32_bf16 v[18:21], v[206:209], v[182:185], v[18:21]
	v_mfma_f32_16x16x32_bf16 v[10:13], v[198:201], v[190:193], v[10:13]
	v_mfma_f32_16x16x32_bf16 v[2:5], v[206:209], v[190:193], v[2:5]
	s_add_i32 s75, 0, 0x18000
	s_barrier
	v_add_u32 v142, s51, v1
	s_nop 0
	v_add_u32_e32 v158, s75, v142
	ds_read_b128 v[142:145], v158
	ds_read_b128 v[146:149], v158 offset:1024
	ds_read_b128 v[150:153], v158 offset:2048
	ds_read_b128 v[158:161], v158 offset:3072
	s_add_u32 s46, s46, 0x40000
	s_addc_u32 s47, s47, 0
	s_mov_b32 m0, s48
	v_add_u32 v162, s50, v1
	v_lshl_add_u64 v[194:195], s[46:47], 0, v[136:137]
	v_add_u32_e32 v190, 0, v162
	ds_read_b128 v[162:165], v190 offset:32768
	ds_read_b128 v[166:169], v190 offset:33792
	ds_read_b128 v[170:173], v190 offset:34816
	ds_read_b128 v[174:177], v190 offset:35840
	ds_read_b128 v[178:181], v190 offset:36864
	ds_read_b128 v[182:185], v190 offset:37888
	ds_read_b128 v[186:189], v190 offset:38912
	ds_read_b128 v[190:193], v190 offset:39936
	global_load_lds_dwordx4 v[194:195], off
	v_lshl_add_u64 v[194:195], s[46:47], 0, v[132:133]
	s_mov_b32 m0, s49
	s_nop 0
	global_load_lds_dwordx4 v[194:195], off
	s_waitcnt lgkmcnt(8)
	s_barrier
	s_waitcnt lgkmcnt(0)
	s_waitcnt lgkmcnt(0)
	v_mfma_f32_16x16x32_bf16 v[126:129], v[142:145], v[162:165], v[126:129]
	v_mfma_f32_16x16x32_bf16 v[118:121], v[150:153], v[162:165], v[118:121]
	v_mfma_f32_16x16x32_bf16 v[110:113], v[142:145], v[170:173], v[110:113]
	v_mfma_f32_16x16x32_bf16 v[102:105], v[150:153], v[170:173], v[102:105]
	v_mfma_f32_16x16x32_bf16 v[94:97], v[142:145], v[178:181], v[94:97]
	v_mfma_f32_16x16x32_bf16 v[86:89], v[150:153], v[178:181], v[86:89]
	v_mfma_f32_16x16x32_bf16 v[78:81], v[142:145], v[186:189], v[78:81]
	v_mfma_f32_16x16x32_bf16 v[70:73], v[150:153], v[186:189], v[70:73]
	v_mfma_f32_16x16x32_bf16 v[126:129], v[146:149], v[166:169], v[126:129]
	v_mfma_f32_16x16x32_bf16 v[118:121], v[158:161], v[166:169], v[118:121]
	v_mfma_f32_16x16x32_bf16 v[110:113], v[146:149], v[174:177], v[110:113]
	v_mfma_f32_16x16x32_bf16 v[102:105], v[158:161], v[174:177], v[102:105]
	v_mfma_f32_16x16x32_bf16 v[94:97], v[146:149], v[182:185], v[94:97]
	v_mfma_f32_16x16x32_bf16 v[86:89], v[158:161], v[182:185], v[86:89]
	v_mfma_f32_16x16x32_bf16 v[78:81], v[146:149], v[190:193], v[78:81]
	v_mfma_f32_16x16x32_bf16 v[70:73], v[158:161], v[190:193], v[70:73]
	s_barrier
	s_add_i32 s46, 0, 0x1c000
	s_add_i32 s47, s75, s11
	v_add_u32 v194, s51, v1
	v_lshl_add_u64 v[212:213], v[212:213], 0, s[30:31]
	v_add_u32_e32 v206, s46, v194
	s_mov_b32 m0, s47
	ds_read_b128 v[194:197], v206
	ds_read_b128 v[198:201], v206 offset:1024
	ds_read_b128 v[202:205], v206 offset:2048
	ds_read_b128 v[206:209], v206 offset:3072
	global_load_lds_dwordx4 v[212:213], off
	v_lshl_add_u64 v[212:213], v[214:215], 0, s[30:31]
	s_add_i32 m0, s47, 0x2000
	s_nop 0
	global_load_lds_dwordx4 v[212:213], off
	s_barrier
	s_waitcnt lgkmcnt(0)
	s_waitcnt lgkmcnt(0)
	v_mfma_f32_16x16x32_bf16 v[122:125], v[194:197], v[162:165], v[122:125]
	v_mfma_f32_16x16x32_bf16 v[114:117], v[202:205], v[162:165], v[114:117]
	v_mfma_f32_16x16x32_bf16 v[106:109], v[194:197], v[170:173], v[106:109]
	v_mfma_f32_16x16x32_bf16 v[98:101], v[202:205], v[170:173], v[98:101]
	v_mfma_f32_16x16x32_bf16 v[90:93], v[194:197], v[178:181], v[90:93]
	v_mfma_f32_16x16x32_bf16 v[82:85], v[202:205], v[178:181], v[82:85]
	v_mfma_f32_16x16x32_bf16 v[74:77], v[194:197], v[186:189], v[74:77]
	v_mfma_f32_16x16x32_bf16 v[66:69], v[202:205], v[186:189], v[66:69]
	v_mfma_f32_16x16x32_bf16 v[122:125], v[198:201], v[166:169], v[122:125]
	v_mfma_f32_16x16x32_bf16 v[114:117], v[206:209], v[166:169], v[114:117]
	v_mfma_f32_16x16x32_bf16 v[106:109], v[198:201], v[174:177], v[106:109]
	v_mfma_f32_16x16x32_bf16 v[98:101], v[206:209], v[174:177], v[98:101]
	v_mfma_f32_16x16x32_bf16 v[90:93], v[198:201], v[182:185], v[90:93]
	v_mfma_f32_16x16x32_bf16 v[82:85], v[206:209], v[182:185], v[82:85]
	v_mfma_f32_16x16x32_bf16 v[74:77], v[198:201], v[190:193], v[74:77]
	v_mfma_f32_16x16x32_bf16 v[66:69], v[206:209], v[190:193], v[66:69]
	s_mov_b32 m0, s52
	s_barrier
; __device__ __forceinline__ unsigned cvt_pk_bf16(float lo, float hi) { const f32x2c f = {lo, hi}; return __builtin_bit_cast(unsigned, __builtin_convertvector(f, bf16x2c)); }
; __device__ __forceinline__ float silu_f(float g) { return g * __builtin_amdgcn_rcpf(1.0f + __expf(-g)); }
; #define PG8_STAGE(bufoff, gbase, voff) do { _Pragma("unroll") for (int _i = 0; _i < 2; ++_i) \
;         __builtin_amdgcn_global_load_lds((const unsigned*)((const char*)(gbase) + (voff)[_i]), (PG8_LAS unsigned*)(lds + (bufoff) + ldsw + _i * 8192), 16, 0, 0); } while (0)
; #define PG8_LDA(dst, b, h) do { int aoff; asm volatile("v_add_u32 %0, %1, %2" : "=v"(aoff) : "s"(ua), "v"(foff)); _Pragma("unroll") for (int m = 0; m < 4; ++m) _Pragma("unroll") for (int k = 0; k < 2; ++k) dst[m][k] = *(const PG8_LAS bf16x8*)(lds + PG8_SA(b, h) + aoff + m * 2048 + k * 1024); } while (0)
; #define PG8_WAIT_V(n) asm volatile("s_waitcnt vmcnt(" #n ")" ::: "memory")
; #define PG8_WAIT_L(n) asm volatile("s_waitcnt lgkmcnt(" #n ")" ::: "memory")
;     __device__ __forceinline__ void operator()(const f32x4 (&acc)[2][2][4][2], const Unit& u, int wr, int wc, int fr, int fq) const {
;         const int row0 = u.pm * BM + wr * 64 + fr; const int col0 = u.pn * HALF + wc * 32 + 8 * fq;
; #pragma unroll
;         for (int ai = 0; ai < 2; ++ai)
; #pragma unroll
;             for (int m = 0; m < 4; ++m) { bf16_t* rowp = H + (size_t)(row0 + ai * HALF + m * 16) * ldh + col0;
;                 const f32x4 g0 = acc[ai][0][m][0], g1 = acc[ai][0][m][1], u0 = acc[ai][1][m][0], u1 = acc[ai][1][m][1];
;                 u32x4 w; w.x = cvt_pk_bf16(silu_f(g0[0]) * u0[0], silu_f(g0[1]) * u0[1]); w.y = cvt_pk_bf16(silu_f(g0[2]) * u0[2], silu_f(g0[3]) * u0[3]);
;                 w.z = cvt_pk_bf16(silu_f(g1[0]) * u1[0], silu_f(g1[1]) * u1[1]); w.w = cvt_pk_bf16(silu_f(g1[2]) * u1[2], silu_f(g1[3]) * u1[3]);
;                 *(u32x4*)rowp = w; }
; template <class Epi, class Sched>
; __device__ __forceinline__ void gemm_phase(PG8_LAS unsigned char* lds, const Gemm g, const Sched& S, const Epi& E) {
;     ...
;             PG8_LDA(At, 1, 1); PG8_STAGE(PG8_SA(1, 0), a3, voffA);
;             PG8_BAR; PG8_WAIT_L(0); PG8_MMA(1, 0, At, B0); PG8_BAR; PG8_SCHED;
;             PG8_STAGE(PG8_SB(1, 1), b3 + hstep, voffB);
;             PG8_WAIT_V(6); PG8_BAR; PG8_MMA(1, 1, At, B1); PG8_BAR;
;         }
	v_add_u32 v162, s50, v1
	v_lshl_add_u64 v[212:213], v[218:219], 0, s[30:31]
	v_add_u32_e32 v190, 0, v162
	ds_read_b128 v[162:165], v190 offset:49152
	ds_read_b128 v[166:169], v190 offset:50176
	ds_read_b128 v[170:173], v190 offset:51200
	ds_read_b128 v[174:177], v190 offset:52224
	ds_read_b128 v[178:181], v190 offset:53248
	ds_read_b128 v[182:185], v190 offset:54272
	ds_read_b128 v[186:189], v190 offset:55296
	ds_read_b128 v[190:193], v190 offset:56320
	global_load_lds_dwordx4 v[212:213], off
	v_lshl_add_u64 v[212:213], v[220:221], 0, s[30:31]
	s_mov_b32 m0, s53
	s_nop 0
	global_load_lds_dwordx4 v[212:213], off
	s_barrier
	s_waitcnt lgkmcnt(0)
	s_waitcnt lgkmcnt(0)
	v_mfma_f32_16x16x32_bf16 v[62:65], v[142:145], v[162:165], v[62:65]
	v_mfma_f32_16x16x32_bf16 v[54:57], v[150:153], v[162:165], v[54:57]
	v_mfma_f32_16x16x32_bf16 v[46:49], v[142:145], v[170:173], v[46:49]
	v_mfma_f32_16x16x32_bf16 v[38:41], v[150:153], v[170:173], v[38:41]
	v_mfma_f32_16x16x32_bf16 v[30:33], v[142:145], v[178:181], v[30:33]
	v_mfma_f32_16x16x32_bf16 v[22:25], v[150:153], v[178:181], v[22:25]
	v_mfma_f32_16x16x32_bf16 v[14:17], v[142:145], v[186:189], v[14:17]
	v_mfma_f32_16x16x32_bf16 v[6:9], v[150:153], v[186:189], v[6:9]
	v_mfma_f32_16x16x32_bf16 v[62:65], v[146:149], v[166:169], v[62:65]
	v_mfma_f32_16x16x32_bf16 v[54:57], v[158:161], v[166:169], v[54:57]
	v_mfma_f32_16x16x32_bf16 v[46:49], v[146:149], v[174:177], v[46:49]
	v_mfma_f32_16x16x32_bf16 v[38:41], v[158:161], v[174:177], v[38:41]
	v_mfma_f32_16x16x32_bf16 v[30:33], v[146:149], v[182:185], v[30:33]
	v_mfma_f32_16x16x32_bf16 v[22:25], v[158:161], v[182:185], v[22:25]
	v_mfma_f32_16x16x32_bf16 v[14:17], v[146:149], v[190:193], v[14:17]
	v_mfma_f32_16x16x32_bf16 v[6:9], v[158:161], v[190:193], v[6:9]
	s_barrier
	s_add_u32 s44, s44, 0x40080
	s_addc_u32 s45, s45, 0
	s_add_i32 s46, s46, s11
	v_lshl_add_u64 v[142:143], s[44:45], 0, v[134:135]
	s_mov_b32 m0, s46
	s_nop 0
	global_load_lds_dwordx4 v[142:143], off
	v_lshl_add_u64 v[142:143], s[44:45], 0, v[130:131]
	s_add_i32 m0, s46, 0x2000
	s_nop 0
	global_load_lds_dwordx4 v[142:143], off
	s_waitcnt vmcnt(6)
	s_barrier
	v_mfma_f32_16x16x32_bf16 v[58:61], v[194:197], v[162:165], v[58:61]
	v_mfma_f32_16x16x32_bf16 v[50:53], v[202:205], v[162:165], v[50:53]
	v_mfma_f32_16x16x32_bf16 v[42:45], v[194:197], v[170:173], v[42:45]
	v_mfma_f32_16x16x32_bf16 v[34:37], v[202:205], v[170:173], v[34:37]
	v_mfma_f32_16x16x32_bf16 v[26:29], v[194:197], v[178:181], v[26:29]
	v_mfma_f32_16x16x32_bf16 v[18:21], v[202:205], v[178:181], v[18:21]
	v_mfma_f32_16x16x32_bf16 v[10:13], v[194:197], v[186:189], v[10:13]
	v_mfma_f32_16x16x32_bf16 v[2:5], v[202:205], v[186:189], v[2:5]
	v_mfma_f32_16x16x32_bf16 v[58:61], v[198:201], v[166:169], v[58:61]
	v_mfma_f32_16x16x32_bf16 v[50:53], v[206:209], v[166:169], v[50:53]
	v_mfma_f32_16x16x32_bf16 v[42:45], v[198:201], v[174:177], v[42:45]
	v_mfma_f32_16x16x32_bf16 v[34:37], v[206:209], v[174:177], v[34:37]
	v_mfma_f32_16x16x32_bf16 v[26:29], v[198:201], v[182:185], v[26:29]
	v_mfma_f32_16x16x32_bf16 v[18:21], v[206:209], v[182:185], v[18:21]
	v_mfma_f32_16x16x32_bf16 v[10:13], v[198:201], v[190:193], v[10:13]
	v_mfma_f32_16x16x32_bf16 v[2:5], v[206:209], v[190:193], v[2:5]
	s_add_i32 s74, s74, 2
	s_add_u32 s26, s26, 0x100
	s_addc_u32 s27, s27, 0
	s_add_u32 s62, s62, 0x100
	s_addc_u32 s63, s63, 0
	s_cmp_gt_u32 s74, 13
	s_barrier
	s_cbranch_scc0 .LBB0_1109
	v_mul_f32_e32 v148, 0xbfb8aa3b, v126
	v_mul_f32_e32 v149, 0xbfb8aa3b, v127
	v_exp_f32_e32 v148, v148
	v_exp_f32_e32 v149, v149
	v_lshl_add_u32 v158, s16, 8, v156
	v_lshl_or_b32 v144, s2, 7, v157
	v_add_f32_e32 v148, 1.0, v148
	v_add_f32_e32 v149, 1.0, v149
	v_rcp_f32_e32 v148, v148
	v_rcp_f32_e32 v149, v149
	v_ashrrev_i32_e32 v145, 31, v144
	v_mov_b64_e32 v[142:143], s[68:69]
	s_movk_i32 s2, 0x1600
	v_pk_mul_f32 v[126:127], v[126:127], v[148:149]
	v_mad_i64_i32 v[146:147], s[26:27], v158, s2, v[142:143]
	v_pk_mul_f32 v[122:123], v[126:127], v[122:123]
	v_lshlrev_b64 v[144:145], 1, v[144:145]
	v_cvt_pk_bf16_f32 v122, v122, v123
	v_mul_f32_e32 v123, 0xbfb8aa3b, v128
	v_exp_f32_e32 v123, v123
	v_lshl_add_u64 v[146:147], v[146:147], 0, v[144:145]
	s_and_b64 vcc, exec, s[38:39]
	s_mov_b32 s16, s20
	v_add_f32_e32 v123, 1.0, v123
	v_rcp_f32_e32 v126, v123
	v_mul_f32_e32 v123, 0xbfb8aa3b, v129
	v_exp_f32_e32 v123, v123
	s_mov_b64 s[44:45], s[28:29]
	v_add_f32_e32 v123, 1.0, v123
	v_rcp_f32_e32 v127, v123
	s_nop 0
	v_pk_mul_f32 v[126:127], v[128:129], v[126:127]
	s_nop 0
	v_pk_mul_f32 v[124:125], v[126:127], v[124:125]
	s_nop 0
	v_cvt_pk_bf16_f32 v123, v124, v125
	v_mul_f32_e32 v124, 0xbfb8aa3b, v118
	v_mul_f32_e32 v125, 0xbfb8aa3b, v119
	v_exp_f32_e32 v124, v124
	v_exp_f32_e32 v125, v125
	v_add_f32_e32 v124, 1.0, v124
	v_add_f32_e32 v125, 1.0, v125
	v_rcp_f32_e32 v124, v124
	v_rcp_f32_e32 v125, v125
	s_nop 0
	v_pk_mul_f32 v[118:119], v[118:119], v[124:125]
	s_nop 0
	v_pk_mul_f32 v[114:115], v[118:119], v[114:115]
	s_nop 0
	v_cvt_pk_bf16_f32 v124, v114, v115
	v_mul_f32_e32 v114, 0xbfb8aa3b, v120
	v_mul_f32_e32 v115, 0xbfb8aa3b, v121
	v_exp_f32_e32 v114, v114
	v_exp_f32_e32 v115, v115
	v_add_f32_e32 v114, 1.0, v114
	v_add_f32_e32 v115, 1.0, v115
	v_rcp_f32_e32 v114, v114
	v_rcp_f32_e32 v115, v115
	s_nop 0
	v_pk_mul_f32 v[114:115], v[120:121], v[114:115]
	s_nop 0
	v_pk_mul_f32 v[114:115], v[114:115], v[116:117]
	v_mul_f32_e32 v116, 0xbfb8aa3b, v110
	v_mul_f32_e32 v117, 0xbfb8aa3b, v111
	v_exp_f32_e32 v116, v116
	v_exp_f32_e32 v117, v117
	v_cvt_pk_bf16_f32 v125, v114, v115
	v_or_b32_e32 v114, 16, v158
	v_add_f32_e32 v116, 1.0, v116
	v_add_f32_e32 v117, 1.0, v117
	v_rcp_f32_e32 v116, v116
; __device__ __forceinline__ unsigned cvt_pk_bf16(float lo, float hi) { const f32x2c f = {lo, hi}; return __builtin_bit_cast(unsigned, __builtin_convertvector(f, bf16x2c)); }
; __device__ __forceinline__ float silu_f(float g) { return g * __builtin_amdgcn_rcpf(1.0f + __expf(-g)); }
;     __device__ __forceinline__ void operator()(const f32x4 (&acc)[2][2][4][2], const Unit& u, int wr, int wc, int fr, int fq) const {
;         const int row0 = u.pm * BM + wr * 64 + fr; const int col0 = u.pn * HALF + wc * 32 + 8 * fq;
; #pragma unroll
;         for (int ai = 0; ai < 2; ++ai)
; #pragma unroll
;             for (int m = 0; m < 4; ++m) { bf16_t* rowp = H + (size_t)(row0 + ai * HALF + m * 16) * ldh + col0;
;                 const f32x4 g0 = acc[ai][0][m][0], g1 = acc[ai][0][m][1], u0 = acc[ai][1][m][0], u1 = acc[ai][1][m][1];
;                 u32x4 w; w.x = cvt_pk_bf16(silu_f(g0[0]) * u0[0], silu_f(g0[1]) * u0[1]); w.y = cvt_pk_bf16(silu_f(g0[2]) * u0[2], silu_f(g0[3]) * u0[3]);
;                 w.z = cvt_pk_bf16(silu_f(g1[0]) * u1[0], silu_f(g1[1]) * u1[1]); w.w = cvt_pk_bf16(silu_f(g1[2]) * u1[2], silu_f(g1[3]) * u1[3]);
;                 *(u32x4*)rowp = w; }
	v_rcp_f32_e32 v117, v117
	v_mad_i64_i32 v[114:115], s[26:27], v114, s2, v[142:143]
	v_lshl_add_u64 v[114:115], v[114:115], 0, v[144:145]
	v_pk_mul_f32 v[110:111], v[110:111], v[116:117]
	global_store_dwordx4 v[146:147], v[122:125], off
	v_pk_mul_f32 v[106:107], v[110:111], v[106:107]
	s_nop 0
	v_cvt_pk_bf16_f32 v106, v106, v107
	v_mul_f32_e32 v107, 0xbfb8aa3b, v112
	v_exp_f32_e32 v107, v107
	s_nop 0
	v_add_f32_e32 v107, 1.0, v107
	v_rcp_f32_e32 v110, v107
	v_mul_f32_e32 v107, 0xbfb8aa3b, v113
	v_exp_f32_e32 v107, v107
	s_nop 0
	v_add_f32_e32 v107, 1.0, v107
	v_rcp_f32_e32 v111, v107
	s_nop 0
	v_pk_mul_f32 v[110:111], v[112:113], v[110:111]
	s_nop 0
	v_pk_mul_f32 v[108:109], v[110:111], v[108:109]
	s_nop 0
	v_cvt_pk_bf16_f32 v107, v108, v109
	v_mul_f32_e32 v108, 0xbfb8aa3b, v102
	v_mul_f32_e32 v109, 0xbfb8aa3b, v103
	v_exp_f32_e32 v108, v108
	v_exp_f32_e32 v109, v109
	v_add_f32_e32 v108, 1.0, v108
	v_add_f32_e32 v109, 1.0, v109
	v_rcp_f32_e32 v108, v108
	v_rcp_f32_e32 v109, v109
	s_nop 0
	v_pk_mul_f32 v[102:103], v[102:103], v[108:109]
	s_nop 0
	v_pk_mul_f32 v[98:99], v[102:103], v[98:99]
	s_nop 0
	v_cvt_pk_bf16_f32 v108, v98, v99
	v_mul_f32_e32 v98, 0xbfb8aa3b, v104
	v_mul_f32_e32 v99, 0xbfb8aa3b, v105
	v_exp_f32_e32 v98, v98
	v_exp_f32_e32 v99, v99
	v_add_f32_e32 v98, 1.0, v98
	v_add_f32_e32 v99, 1.0, v99
	v_rcp_f32_e32 v98, v98
	v_rcp_f32_e32 v99, v99
	s_nop 0
	v_pk_mul_f32 v[98:99], v[104:105], v[98:99]
	s_nop 0
	v_pk_mul_f32 v[98:99], v[98:99], v[100:101]
	v_mul_f32_e32 v100, 0xbfb8aa3b, v94
	v_mul_f32_e32 v101, 0xbfb8aa3b, v95
	v_exp_f32_e32 v100, v100
	v_exp_f32_e32 v101, v101
	v_cvt_pk_bf16_f32 v109, v98, v99
	v_or_b32_e32 v98, 32, v158
	v_add_f32_e32 v100, 1.0, v100
	v_add_f32_e32 v101, 1.0, v101
	v_rcp_f32_e32 v100, v100
	v_rcp_f32_e32 v101, v101
	v_mad_i64_i32 v[98:99], s[26:27], v98, s2, v[142:143]
	v_lshl_add_u64 v[98:99], v[98:99], 0, v[144:145]
	v_pk_mul_f32 v[94:95], v[94:95], v[100:101]
	global_store_dwordx4 v[114:115], v[106:109], off
	v_pk_mul_f32 v[90:91], v[94:95], v[90:91]
	s_nop 0
	v_cvt_pk_bf16_f32 v90, v90, v91
	v_mul_f32_e32 v91, 0xbfb8aa3b, v96
	v_exp_f32_e32 v91, v91
	s_nop 0
	v_add_f32_e32 v91, 1.0, v91
	v_rcp_f32_e32 v94, v91
	v_mul_f32_e32 v91, 0xbfb8aa3b, v97
	v_exp_f32_e32 v91, v91
	s_nop 0
	v_add_f32_e32 v91, 1.0, v91
	v_rcp_f32_e32 v95, v91
	s_nop 0
	v_pk_mul_f32 v[94:95], v[96:97], v[94:95]
	s_nop 0
	v_pk_mul_f32 v[92:93], v[94:95], v[92:93]
	s_nop 0
	v_cvt_pk_bf16_f32 v91, v92, v93
	v_mul_f32_e32 v92, 0xbfb8aa3b, v86
	v_mul_f32_e32 v93, 0xbfb8aa3b, v87
	v_exp_f32_e32 v92, v92
	v_exp_f32_e32 v93, v93
	v_add_f32_e32 v92, 1.0, v92
	v_add_f32_e32 v93, 1.0, v93
	v_rcp_f32_e32 v92, v92
	v_rcp_f32_e32 v93, v93
	s_nop 0
	v_pk_mul_f32 v[86:87], v[86:87], v[92:93]
	s_nop 0
	v_pk_mul_f32 v[82:83], v[86:87], v[82:83]
	s_nop 0
	v_cvt_pk_bf16_f32 v92, v82, v83
	v_mul_f32_e32 v82, 0xbfb8aa3b, v88
	v_mul_f32_e32 v83, 0xbfb8aa3b, v89
	v_exp_f32_e32 v82, v82
	v_exp_f32_e32 v83, v83
	v_add_f32_e32 v82, 1.0, v82
	v_add_f32_e32 v83, 1.0, v83
	v_rcp_f32_e32 v82, v82
	v_rcp_f32_e32 v83, v83
	s_nop 0
	v_pk_mul_f32 v[82:83], v[88:89], v[82:83]
	s_nop 0
	v_pk_mul_f32 v[82:83], v[82:83], v[84:85]
	v_mul_f32_e32 v84, 0xbfb8aa3b, v78
	v_mul_f32_e32 v85, 0xbfb8aa3b, v79
	v_exp_f32_e32 v84, v84
	v_exp_f32_e32 v85, v85
	v_cvt_pk_bf16_f32 v93, v82, v83
	v_or_b32_e32 v82, 48, v158
	v_add_f32_e32 v84, 1.0, v84
	v_add_f32_e32 v85, 1.0, v85
	v_rcp_f32_e32 v84, v84
	v_rcp_f32_e32 v85, v85
	v_mad_i64_i32 v[82:83], s[26:27], v82, s2, v[142:143]
	v_lshl_add_u64 v[82:83], v[82:83], 0, v[144:145]
	v_pk_mul_f32 v[78:79], v[78:79], v[84:85]
	global_store_dwordx4 v[98:99], v[90:93], off
	v_pk_mul_f32 v[74:75], v[78:79], v[74:75]
	s_nop 0
	v_cvt_pk_bf16_f32 v74, v74, v75
	v_mul_f32_e32 v75, 0xbfb8aa3b, v80
	v_exp_f32_e32 v75, v75
	s_nop 0
	v_add_f32_e32 v75, 1.0, v75
	v_rcp_f32_e32 v78, v75
	v_mul_f32_e32 v75, 0xbfb8aa3b, v81
	v_exp_f32_e32 v75, v75
	s_nop 0
	v_add_f32_e32 v75, 1.0, v75
	v_rcp_f32_e32 v79, v75
	s_nop 0
	v_pk_mul_f32 v[78:79], v[80:81], v[78:79]
	s_nop 0
	v_pk_mul_f32 v[76:77], v[78:79], v[76:77]
	s_nop 0
	v_cvt_pk_bf16_f32 v75, v76, v77
	v_mul_f32_e32 v76, 0xbfb8aa3b, v70
	v_mul_f32_e32 v77, 0xbfb8aa3b, v71
	v_exp_f32_e32 v76, v76
	v_exp_f32_e32 v77, v77
	v_add_f32_e32 v76, 1.0, v76
	v_add_f32_e32 v77, 1.0, v77
	v_rcp_f32_e32 v76, v76
	v_rcp_f32_e32 v77, v77
	s_nop 0
	v_pk_mul_f32 v[70:71], v[70:71], v[76:77]
	s_nop 0
	v_pk_mul_f32 v[66:67], v[70:71], v[66:67]
	s_nop 0
	v_cvt_pk_bf16_f32 v76, v66, v67
	v_mul_f32_e32 v66, 0xbfb8aa3b, v72
	v_mul_f32_e32 v67, 0xbfb8aa3b, v73
	v_exp_f32_e32 v66, v66
	v_exp_f32_e32 v67, v67
	v_add_f32_e32 v66, 1.0, v66
	v_add_f32_e32 v67, 1.0, v67
	v_rcp_f32_e32 v66, v66
	v_rcp_f32_e32 v67, v67
	s_nop 0
	v_pk_mul_f32 v[66:67], v[72:73], v[66:67]
	s_nop 0
	v_pk_mul_f32 v[66:67], v[66:67], v[68:69]
	v_mul_f32_e32 v68, 0xbfb8aa3b, v62
	v_mul_f32_e32 v69, 0xbfb8aa3b, v63
	v_exp_f32_e32 v68, v68
	v_exp_f32_e32 v69, v69
	v_cvt_pk_bf16_f32 v77, v66, v67
	v_add_u32_e32 v66, 0x80, v158
	v_add_f32_e32 v68, 1.0, v68
	v_add_f32_e32 v69, 1.0, v69
	v_rcp_f32_e32 v68, v68
	v_rcp_f32_e32 v69, v69
	v_mad_i64_i32 v[66:67], s[26:27], v66, s2, v[142:143]
	v_lshl_add_u64 v[66:67], v[66:67], 0, v[144:145]
	v_pk_mul_f32 v[62:63], v[62:63], v[68:69]
	global_store_dwordx4 v[82:83], v[74:77], off
	v_pk_mul_f32 v[58:59], v[62:63], v[58:59]
	s_nop 0
	v_cvt_pk_bf16_f32 v58, v58, v59
	v_mul_f32_e32 v59, 0xbfb8aa3b, v64
	v_exp_f32_e32 v59, v59
	s_nop 0
	v_add_f32_e32 v59, 1.0, v59
	v_rcp_f32_e32 v62, v59
	v_mul_f32_e32 v59, 0xbfb8aa3b, v65
	v_exp_f32_e32 v59, v59
	s_nop 0
	v_add_f32_e32 v59, 1.0, v59
	v_rcp_f32_e32 v63, v59
	s_nop 0
; __device__ __forceinline__ unsigned cvt_pk_bf16(float lo, float hi) { const f32x2c f = {lo, hi}; return __builtin_bit_cast(unsigned, __builtin_convertvector(f, bf16x2c)); }
; __device__ __forceinline__ float silu_f(float g) { return g * __builtin_amdgcn_rcpf(1.0f + __expf(-g)); }
; #define PG8_WAIT_V(n) asm volatile("s_waitcnt vmcnt(" #n ")" ::: "memory")
; #define PG8_BAR __builtin_amdgcn_s_barrier()
;     __device__ __forceinline__ void operator()(const f32x4 (&acc)[2][2][4][2], const Unit& u, int wr, int wc, int fr, int fq) const {
;         const int row0 = u.pm * BM + wr * 64 + fr; const int col0 = u.pn * HALF + wc * 32 + 8 * fq;
; #pragma unroll
;         for (int ai = 0; ai < 2; ++ai)
; #pragma unroll
;             for (int m = 0; m < 4; ++m) { bf16_t* rowp = H + (size_t)(row0 + ai * HALF + m * 16) * ldh + col0;
;                 const f32x4 g0 = acc[ai][0][m][0], g1 = acc[ai][0][m][1], u0 = acc[ai][1][m][0], u1 = acc[ai][1][m][1];
;                 u32x4 w; w.x = cvt_pk_bf16(silu_f(g0[0]) * u0[0], silu_f(g0[1]) * u0[1]); w.y = cvt_pk_bf16(silu_f(g0[2]) * u0[2], silu_f(g0[3]) * u0[3]);
;                 w.z = cvt_pk_bf16(silu_f(g1[0]) * u1[0], silu_f(g1[1]) * u1[1]); w.w = cvt_pk_bf16(silu_f(g1[2]) * u1[2], silu_f(g1[3]) * u1[3]);
;                 *(u32x4*)rowp = w; }
; template <class Epi, class Sched>
; __device__ __forceinline__ void gemm_phase(PG8_LAS unsigned char* lds, const Gemm g, const Sched& S, const Epi& E) {
;     ...
;     PG8_WAIT_V(0);
;     if (wr == 0) PG8_BAR;
;     PG8_BAR;
	v_pk_mul_f32 v[62:63], v[64:65], v[62:63]
	s_nop 0
	v_pk_mul_f32 v[60:61], v[62:63], v[60:61]
	s_nop 0
	v_cvt_pk_bf16_f32 v59, v60, v61
	v_mul_f32_e32 v60, 0xbfb8aa3b, v54
	v_mul_f32_e32 v61, 0xbfb8aa3b, v55
	v_exp_f32_e32 v60, v60
	v_exp_f32_e32 v61, v61
	v_add_f32_e32 v60, 1.0, v60
	v_add_f32_e32 v61, 1.0, v61
	v_rcp_f32_e32 v60, v60
	v_rcp_f32_e32 v61, v61
	s_nop 0
	v_pk_mul_f32 v[54:55], v[54:55], v[60:61]
	s_nop 0
	v_pk_mul_f32 v[50:51], v[54:55], v[50:51]
	s_nop 0
	v_cvt_pk_bf16_f32 v60, v50, v51
	v_mul_f32_e32 v50, 0xbfb8aa3b, v56
	v_mul_f32_e32 v51, 0xbfb8aa3b, v57
	v_exp_f32_e32 v50, v50
	v_exp_f32_e32 v51, v51
	v_add_f32_e32 v50, 1.0, v50
	v_add_f32_e32 v51, 1.0, v51
	v_rcp_f32_e32 v50, v50
	v_rcp_f32_e32 v51, v51
	s_nop 0
	v_pk_mul_f32 v[50:51], v[56:57], v[50:51]
	s_nop 0
	v_pk_mul_f32 v[50:51], v[50:51], v[52:53]
	v_mul_f32_e32 v52, 0xbfb8aa3b, v46
	v_mul_f32_e32 v53, 0xbfb8aa3b, v47
	v_exp_f32_e32 v52, v52
	v_exp_f32_e32 v53, v53
	v_cvt_pk_bf16_f32 v61, v50, v51
	v_add_u32_e32 v50, 0x90, v158
	v_add_f32_e32 v52, 1.0, v52
	v_add_f32_e32 v53, 1.0, v53
	v_rcp_f32_e32 v52, v52
	v_rcp_f32_e32 v53, v53
	v_mad_i64_i32 v[50:51], s[26:27], v50, s2, v[142:143]
	v_lshl_add_u64 v[50:51], v[50:51], 0, v[144:145]
	v_pk_mul_f32 v[46:47], v[46:47], v[52:53]
	global_store_dwordx4 v[66:67], v[58:61], off
	v_pk_mul_f32 v[42:43], v[46:47], v[42:43]
	s_nop 0
	v_cvt_pk_bf16_f32 v42, v42, v43
	v_mul_f32_e32 v43, 0xbfb8aa3b, v48
	v_exp_f32_e32 v43, v43
	s_nop 0
	v_add_f32_e32 v43, 1.0, v43
	v_rcp_f32_e32 v46, v43
	v_mul_f32_e32 v43, 0xbfb8aa3b, v49
	v_exp_f32_e32 v43, v43
	s_nop 0
	v_add_f32_e32 v43, 1.0, v43
	v_rcp_f32_e32 v47, v43
	s_nop 0
	v_pk_mul_f32 v[46:47], v[48:49], v[46:47]
	s_nop 0
	v_pk_mul_f32 v[44:45], v[46:47], v[44:45]
	s_nop 0
	v_cvt_pk_bf16_f32 v43, v44, v45
	v_mul_f32_e32 v44, 0xbfb8aa3b, v38
	v_mul_f32_e32 v45, 0xbfb8aa3b, v39
	v_exp_f32_e32 v44, v44
	v_exp_f32_e32 v45, v45
	v_add_f32_e32 v44, 1.0, v44
	v_add_f32_e32 v45, 1.0, v45
	v_rcp_f32_e32 v44, v44
	v_rcp_f32_e32 v45, v45
	s_nop 0
	v_pk_mul_f32 v[38:39], v[38:39], v[44:45]
	s_nop 0
	v_pk_mul_f32 v[34:35], v[38:39], v[34:35]
	s_nop 0
	v_cvt_pk_bf16_f32 v44, v34, v35
	v_mul_f32_e32 v34, 0xbfb8aa3b, v40
	v_mul_f32_e32 v35, 0xbfb8aa3b, v41
	v_exp_f32_e32 v34, v34
	v_exp_f32_e32 v35, v35
	v_add_f32_e32 v34, 1.0, v34
	v_add_f32_e32 v35, 1.0, v35
	v_rcp_f32_e32 v34, v34
	v_rcp_f32_e32 v35, v35
	s_nop 0
	v_pk_mul_f32 v[34:35], v[40:41], v[34:35]
	s_nop 0
	v_pk_mul_f32 v[34:35], v[34:35], v[36:37]
	v_mul_f32_e32 v36, 0xbfb8aa3b, v30
	v_mul_f32_e32 v37, 0xbfb8aa3b, v31
	v_exp_f32_e32 v36, v36
	v_exp_f32_e32 v37, v37
	v_cvt_pk_bf16_f32 v45, v34, v35
	v_add_u32_e32 v34, 0xa0, v158
	v_add_f32_e32 v36, 1.0, v36
	v_add_f32_e32 v37, 1.0, v37
	v_rcp_f32_e32 v36, v36
	v_rcp_f32_e32 v37, v37
	v_mad_i64_i32 v[34:35], s[26:27], v34, s2, v[142:143]
	v_lshl_add_u64 v[34:35], v[34:35], 0, v[144:145]
	v_pk_mul_f32 v[30:31], v[30:31], v[36:37]
	global_store_dwordx4 v[50:51], v[42:45], off
	v_pk_mul_f32 v[26:27], v[30:31], v[26:27]
	s_nop 0
	v_cvt_pk_bf16_f32 v26, v26, v27
	v_mul_f32_e32 v27, 0xbfb8aa3b, v32
	v_exp_f32_e32 v27, v27
	s_nop 0
	v_add_f32_e32 v27, 1.0, v27
	v_rcp_f32_e32 v30, v27
	v_mul_f32_e32 v27, 0xbfb8aa3b, v33
	v_exp_f32_e32 v27, v27
	s_nop 0
	v_add_f32_e32 v27, 1.0, v27
	v_rcp_f32_e32 v31, v27
	s_nop 0
	v_pk_mul_f32 v[30:31], v[32:33], v[30:31]
	s_nop 0
	v_pk_mul_f32 v[28:29], v[30:31], v[28:29]
	s_nop 0
	v_cvt_pk_bf16_f32 v27, v28, v29
	v_mul_f32_e32 v28, 0xbfb8aa3b, v22
	v_mul_f32_e32 v29, 0xbfb8aa3b, v23
	v_exp_f32_e32 v28, v28
	v_exp_f32_e32 v29, v29
	v_add_f32_e32 v28, 1.0, v28
	v_add_f32_e32 v29, 1.0, v29
	v_rcp_f32_e32 v28, v28
	v_rcp_f32_e32 v29, v29
	s_nop 0
	v_pk_mul_f32 v[22:23], v[22:23], v[28:29]
	s_nop 0
	v_pk_mul_f32 v[18:19], v[22:23], v[18:19]
	s_nop 0
	v_cvt_pk_bf16_f32 v28, v18, v19
	v_mul_f32_e32 v18, 0xbfb8aa3b, v24
	v_mul_f32_e32 v19, 0xbfb8aa3b, v25
	v_exp_f32_e32 v18, v18
	v_exp_f32_e32 v19, v19
	v_add_f32_e32 v18, 1.0, v18
	v_add_f32_e32 v19, 1.0, v19
	v_rcp_f32_e32 v18, v18
	v_rcp_f32_e32 v19, v19
	s_nop 0
	v_pk_mul_f32 v[18:19], v[24:25], v[18:19]
	s_nop 0
	v_pk_mul_f32 v[18:19], v[18:19], v[20:21]
	v_mul_f32_e32 v20, 0xbfb8aa3b, v14
	v_mul_f32_e32 v21, 0xbfb8aa3b, v15
	v_exp_f32_e32 v20, v20
	v_exp_f32_e32 v21, v21
	v_cvt_pk_bf16_f32 v29, v18, v19
	v_add_u32_e32 v18, 0xb0, v158
	v_add_f32_e32 v20, 1.0, v20
	v_add_f32_e32 v21, 1.0, v21
	v_rcp_f32_e32 v20, v20
	v_rcp_f32_e32 v21, v21
	v_mad_i64_i32 v[18:19], s[26:27], v18, s2, v[142:143]
	v_lshl_add_u64 v[18:19], v[18:19], 0, v[144:145]
	v_pk_mul_f32 v[14:15], v[14:15], v[20:21]
	s_mov_b32 s2, s18
	v_pk_mul_f32 v[10:11], v[14:15], v[10:11]
	s_mov_b64 s[26:27], s[24:25]
	v_cvt_pk_bf16_f32 v10, v10, v11
	v_mul_f32_e32 v11, 0xbfb8aa3b, v16
	v_exp_f32_e32 v11, v11
	global_store_dwordx4 v[34:35], v[26:29], off
	v_add_f32_e32 v11, 1.0, v11
	v_rcp_f32_e32 v14, v11
	v_mul_f32_e32 v11, 0xbfb8aa3b, v17
	v_exp_f32_e32 v11, v11
	s_nop 0
	v_add_f32_e32 v11, 1.0, v11
	v_rcp_f32_e32 v15, v11
	s_nop 0
	v_pk_mul_f32 v[14:15], v[16:17], v[14:15]
	s_nop 0
	v_pk_mul_f32 v[12:13], v[14:15], v[12:13]
	s_nop 0
	v_cvt_pk_bf16_f32 v11, v12, v13
	v_mul_f32_e32 v12, 0xbfb8aa3b, v6
	v_mul_f32_e32 v13, 0xbfb8aa3b, v7
	v_exp_f32_e32 v12, v12
	v_exp_f32_e32 v13, v13
	v_add_f32_e32 v12, 1.0, v12
	v_add_f32_e32 v13, 1.0, v13
	v_rcp_f32_e32 v12, v12
	v_rcp_f32_e32 v13, v13
	s_nop 0
	v_pk_mul_f32 v[6:7], v[6:7], v[12:13]
	s_nop 0
	v_pk_mul_f32 v[2:3], v[6:7], v[2:3]
	s_nop 0
	v_cvt_pk_bf16_f32 v12, v2, v3
	v_mul_f32_e32 v2, 0xbfb8aa3b, v8
	v_mul_f32_e32 v3, 0xbfb8aa3b, v9
	v_exp_f32_e32 v2, v2
	v_exp_f32_e32 v3, v3
	v_add_f32_e32 v2, 1.0, v2
	v_add_f32_e32 v3, 1.0, v3
	v_rcp_f32_e32 v2, v2
	v_rcp_f32_e32 v3, v3
	s_nop 0
	v_pk_mul_f32 v[2:3], v[8:9], v[2:3]
	s_nop 0
	v_pk_mul_f32 v[2:3], v[2:3], v[4:5]
	s_nop 0
	v_cvt_pk_bf16_f32 v13, v2, v3
	global_store_dwordx4 v[18:19], v[10:13], off
	s_cbranch_vccz .LBB0_1106
	s_waitcnt vmcnt(0)
	v_readlane_b32 s12, v255, 32
	v_readlane_b32 s52, v255, 35
	v_readlane_b32 s60, v255, 37
	s_cmpk_gt_u32 s8, 0xff
	v_readlane_b32 s13, v255, 33
	v_readlane_b32 s53, v255, 36
	v_readlane_b32 s61, v255, 38
	s_cbranch_scc1 .LBB0_1113
	s_barrier

; #define PG8_STAGE(bufoff, gbase, voff) do { _Pragma("unroll") for (int _i = 0; _i < 2; ++_i) \
;         __builtin_amdgcn_global_load_lds((const unsigned*)((const char*)(gbase) + (voff)[_i]), (PG8_LAS unsigned*)(lds + (bufoff) + ldsw + _i * 8192), 16, 0, 0); } while (0)
; #define PG8_LDA(dst, b, h) do { int aoff; asm volatile("v_add_u32 %0, %1, %2" : "=v"(aoff) : "s"(ua), "v"(foff)); _Pragma("unroll") for (int m = 0; m < 4; ++m) _Pragma("unroll") for (int k = 0; k < 2; ++k) dst[m][k] = *(const PG8_LAS bf16x8*)(lds + PG8_SA(b, h) + aoff + m * 2048 + k * 1024); } while (0)
; #define PG8_LDB(dst, b, h) do { int boff; asm volatile("v_add_u32 %0, %1, %2" : "=v"(boff) : "s"(ub), "v"(foff)); _Pragma("unroll") for (int n = 0; n < 2; ++n) _Pragma("unroll") for (int k = 0; k < 2; ++k) dst[n][k] = *(const PG8_LAS bf16x8*)(lds + PG8_SB(b, h) + boff + n * 2048 + k * 1024); } while (0)
; #define PG8_MMA(ai, bj, At, Bt) do { __builtin_amdgcn_s_setprio(1); _Pragma("unroll") for (int m = 0; m < 4; ++m) _Pragma("unroll") for (int n = 0; n < 2; ++n) _Pragma("unroll") for (int k = 0; k < 2; ++k) \
;         acc[ai][bj][m][n] = __builtin_amdgcn_mfma_f32_16x16x32_bf16(Bt[n][k], At[m][k], acc[ai][bj][m][n], 0, 0, 0); __builtin_amdgcn_s_setprio(0); } while (0)
; #define PG8_WAIT_L(n) asm volatile("s_waitcnt lgkmcnt(" #n ")" ::: "memory")
; #define PG8_BAR __builtin_amdgcn_s_barrier()
; template <class Epi, class Sched>
; __device__ __forceinline__ void gemm_phase(PG8_LAS unsigned char* lds, const Gemm g, const Sched& S, const Epi& E) {
;     ...
;             const bool last = (t == cnt - 2);
;             const char* a1 = cA + (size_t)(t + 1) * kstep;
;             const char* a2 = last ? nA : cA + (size_t)(t + 2) * kstep; const char* b2 = last ? nB : cB + (size_t)(t + 2) * kstep;
;             const char* a3 = a2 + kstep; const char* b3 = b2 + kstep;
;             if (last && has_next) S.a_ready(nxt);
;             PG8_LDB(B0, 0, 0); PG8_SCHED; PG8_LDA(At, 0, 0); PG8_STAGE(PG8_SA(1, 1), a1 + hstep, voffA);
;             PG8_WAIT_L(8); PG8_BAR; PG8_WAIT_L(0); PG8_MMA(0, 0, At, B0); PG8_BAR; PG8_SCHED;
;             PG8_LDB(B1, 0, 1); PG8_STAGE(PG8_SB(0, 0), b2, voffB);
;             PG8_BAR; PG8_WAIT_L(0); PG8_MMA(0, 1, At, B1); PG8_BAR;
;             PG8_LDA(At, 0, 1); PG8_STAGE(PG8_SA(0, 0), a2, voffA);
;             PG8_BAR; PG8_WAIT_L(0); PG8_MMA(1, 0, At, B0); PG8_BAR; PG8_SCHED;
.LBB0_1195:
	s_add_i32 s54, s26, 2
	s_add_u32 s16, s2, 0x100
	s_addc_u32 s17, s3, 0
	s_add_i32 s78, 0, 0x10000
	v_add_u32 v130, s53, v1
	s_cmp_eq_u32 s5, s26
	v_add_u32_e32 v142, s78, v130
	ds_read_b128 v[130:133], v142
	ds_read_b128 v[134:137], v142 offset:1024
	ds_read_b128 v[138:141], v142 offset:2048
	ds_read_b128 v[142:145], v142 offset:3072
	s_cselect_b32 s26, s38, s21
	s_cselect_b32 s47, s45, s17
	s_cselect_b32 s46, s44, s16
	s_cselect_b32 s27, s39, s25
	v_add_u32 v146, s52, v1
	v_lshl_add_u64 v[194:195], s[2:3], 0, v[164:165]
	v_add_u32_e32 v169, 0, v146
	s_add_i32 m0, s12, 0xc000
	ds_read_b128 v[146:149], v169
	ds_read_b128 v[150:153], v169 offset:1024
	ds_read_b128 v[170:173], v169 offset:2048
	ds_read_b128 v[174:177], v169 offset:3072
	ds_read_b128 v[178:181], v169 offset:4096
	ds_read_b128 v[182:185], v169 offset:5120
	ds_read_b128 v[186:189], v169 offset:6144
	ds_read_b128 v[190:193], v169 offset:7168
	global_load_lds_dwordx4 v[194:195], off
	v_lshl_add_u64 v[194:195], s[2:3], 0, v[166:167]
	s_add_i32 m0, s12, 0xe000
	s_nop 0
	global_load_lds_dwordx4 v[194:195], off
	s_waitcnt lgkmcnt(8)
	s_barrier
	s_waitcnt lgkmcnt(0)
	s_waitcnt lgkmcnt(0)
	v_mfma_f32_16x16x32_bf16 v[126:129], v[130:133], v[146:149], v[126:129]
	v_mfma_f32_16x16x32_bf16 v[122:125], v[138:141], v[146:149], v[122:125]
	v_mfma_f32_16x16x32_bf16 v[118:121], v[130:133], v[170:173], v[118:121]
	v_mfma_f32_16x16x32_bf16 v[114:117], v[138:141], v[170:173], v[114:117]
	v_mfma_f32_16x16x32_bf16 v[106:109], v[130:133], v[178:181], v[106:109]
	v_mfma_f32_16x16x32_bf16 v[98:101], v[138:141], v[178:181], v[98:101]
	v_mfma_f32_16x16x32_bf16 v[90:93], v[130:133], v[186:189], v[90:93]
	v_mfma_f32_16x16x32_bf16 v[82:85], v[138:141], v[186:189], v[82:85]
	v_mfma_f32_16x16x32_bf16 v[126:129], v[134:137], v[150:153], v[126:129]
	v_mfma_f32_16x16x32_bf16 v[122:125], v[142:145], v[150:153], v[122:125]
	v_mfma_f32_16x16x32_bf16 v[118:121], v[134:137], v[174:177], v[118:121]
	v_mfma_f32_16x16x32_bf16 v[114:117], v[142:145], v[174:177], v[114:117]
	v_mfma_f32_16x16x32_bf16 v[106:109], v[134:137], v[182:185], v[106:109]
	v_mfma_f32_16x16x32_bf16 v[98:101], v[142:145], v[182:185], v[98:101]
	v_mfma_f32_16x16x32_bf16 v[90:93], v[134:137], v[190:193], v[90:93]
	v_mfma_f32_16x16x32_bf16 v[82:85], v[142:145], v[190:193], v[82:85]
	s_barrier
	v_add_u32 v169, s53, v1
	s_add_i32 s79, 0, 0x14000
	s_add_i32 s2, s78, s10
	v_add_u32_e32 v169, s79, v169
	v_lshl_add_u64 v[212:213], s[26:27], 0, v[156:157]
	s_mov_b32 m0, s2
	ds_read_b128 v[194:197], v169
	ds_read_b128 v[198:201], v169 offset:1024
	ds_read_b128 v[202:205], v169 offset:2048
	ds_read_b128 v[206:209], v169 offset:3072
	global_load_lds_dwordx4 v[212:213], off
	v_lshl_add_u64 v[214:215], s[26:27], 0, v[158:159]
	s_add_i32 m0, s2, 0x2000
	s_nop 0
	global_load_lds_dwordx4 v[214:215], off
	s_barrier
	s_waitcnt lgkmcnt(0)
	s_waitcnt lgkmcnt(0)
	v_mfma_f32_16x16x32_bf16 v[110:113], v[194:197], v[146:149], v[110:113]
	v_mfma_f32_16x16x32_bf16 v[102:105], v[202:205], v[146:149], v[102:105]
	v_mfma_f32_16x16x32_bf16 v[94:97], v[194:197], v[170:173], v[94:97]
	v_mfma_f32_16x16x32_bf16 v[86:89], v[202:205], v[170:173], v[86:89]
	v_mfma_f32_16x16x32_bf16 v[78:81], v[194:197], v[178:181], v[78:81]
	v_mfma_f32_16x16x32_bf16 v[74:77], v[202:205], v[178:181], v[74:77]
	v_mfma_f32_16x16x32_bf16 v[70:73], v[194:197], v[186:189], v[70:73]
	v_mfma_f32_16x16x32_bf16 v[66:69], v[202:205], v[186:189], v[66:69]
	v_mfma_f32_16x16x32_bf16 v[110:113], v[198:201], v[150:153], v[110:113]
	v_mfma_f32_16x16x32_bf16 v[102:105], v[206:209], v[150:153], v[102:105]
	v_mfma_f32_16x16x32_bf16 v[94:97], v[198:201], v[174:177], v[94:97]
	v_mfma_f32_16x16x32_bf16 v[86:89], v[206:209], v[174:177], v[86:89]
	v_mfma_f32_16x16x32_bf16 v[78:81], v[198:201], v[182:185], v[78:81]
	v_mfma_f32_16x16x32_bf16 v[74:77], v[206:209], v[182:185], v[74:77]
	v_mfma_f32_16x16x32_bf16 v[70:73], v[198:201], v[190:193], v[70:73]
	v_mfma_f32_16x16x32_bf16 v[66:69], v[206:209], v[190:193], v[66:69]
	s_mov_b32 m0, s12
	s_barrier
	v_add_u32 v146, s52, v1
	v_lshl_add_u64 v[218:219], s[46:47], 0, v[156:157]
	v_add_u32_e32 v169, 0, v146
	ds_read_b128 v[146:149], v169 offset:16384
	ds_read_b128 v[150:153], v169 offset:17408
	ds_read_b128 v[170:173], v169 offset:18432
	ds_read_b128 v[174:177], v169 offset:19456
	ds_read_b128 v[178:181], v169 offset:20480
	ds_read_b128 v[182:185], v169 offset:21504
	ds_read_b128 v[186:189], v169 offset:22528
	ds_read_b128 v[190:193], v169 offset:23552
	global_load_lds_dwordx4 v[218:219], off
	v_lshl_add_u64 v[220:221], s[46:47], 0, v[158:159]
	s_mov_b32 m0, s13
	s_nop 0
	global_load_lds_dwordx4 v[220:221], off
	s_barrier
	s_waitcnt lgkmcnt(0)
	s_waitcnt lgkmcnt(0)
	v_mfma_f32_16x16x32_bf16 v[62:65], v[130:133], v[146:149], v[62:65]
	v_mfma_f32_16x16x32_bf16 v[58:61], v[138:141], v[146:149], v[58:61]
	v_mfma_f32_16x16x32_bf16 v[54:57], v[130:133], v[170:173], v[54:57]
	v_mfma_f32_16x16x32_bf16 v[50:53], v[138:141], v[170:173], v[50:53]
	v_mfma_f32_16x16x32_bf16 v[38:41], v[130:133], v[178:181], v[38:41]
	v_mfma_f32_16x16x32_bf16 v[34:37], v[138:141], v[178:181], v[34:37]
	v_mfma_f32_16x16x32_bf16 v[22:25], v[130:133], v[186:189], v[22:25]
	v_mfma_f32_16x16x32_bf16 v[18:21], v[138:141], v[186:189], v[18:21]
	v_mfma_f32_16x16x32_bf16 v[62:65], v[134:137], v[150:153], v[62:65]
	v_mfma_f32_16x16x32_bf16 v[58:61], v[142:145], v[150:153], v[58:61]
	v_mfma_f32_16x16x32_bf16 v[54:57], v[134:137], v[174:177], v[54:57]
	v_mfma_f32_16x16x32_bf16 v[50:53], v[142:145], v[174:177], v[50:53]
	v_mfma_f32_16x16x32_bf16 v[38:41], v[134:137], v[182:185], v[38:41]
	v_mfma_f32_16x16x32_bf16 v[34:37], v[142:145], v[182:185], v[34:37]
	v_mfma_f32_16x16x32_bf16 v[22:25], v[134:137], v[190:193], v[22:25]
	v_mfma_f32_16x16x32_bf16 v[18:21], v[142:145], v[190:193], v[18:21]
	s_barrier
; #define PG8_STAGE(bufoff, gbase, voff) do { _Pragma("unroll") for (int _i = 0; _i < 2; ++_i) \
;         __builtin_amdgcn_global_load_lds((const unsigned*)((const char*)(gbase) + (voff)[_i]), (PG8_LAS unsigned*)(lds + (bufoff) + ldsw + _i * 8192), 16, 0, 0); } while (0)
; #define PG8_LDA(dst, b, h) do { int aoff; asm volatile("v_add_u32 %0, %1, %2" : "=v"(aoff) : "s"(ua), "v"(foff)); _Pragma("unroll") for (int m = 0; m < 4; ++m) _Pragma("unroll") for (int k = 0; k < 2; ++k) dst[m][k] = *(const PG8_LAS bf16x8*)(lds + PG8_SA(b, h) + aoff + m * 2048 + k * 1024); } while (0)
; #define PG8_LDB(dst, b, h) do { int boff; asm volatile("v_add_u32 %0, %1, %2" : "=v"(boff) : "s"(ub), "v"(foff)); _Pragma("unroll") for (int n = 0; n < 2; ++n) _Pragma("unroll") for (int k = 0; k < 2; ++k) dst[n][k] = *(const PG8_LAS bf16x8*)(lds + PG8_SB(b, h) + boff + n * 2048 + k * 1024); } while (0)
; #define PG8_MMA(ai, bj, At, Bt) do { __builtin_amdgcn_s_setprio(1); _Pragma("unroll") for (int m = 0; m < 4; ++m) _Pragma("unroll") for (int n = 0; n < 2; ++n) _Pragma("unroll") for (int k = 0; k < 2; ++k) \
;         acc[ai][bj][m][n] = __builtin_amdgcn_mfma_f32_16x16x32_bf16(Bt[n][k], At[m][k], acc[ai][bj][m][n], 0, 0, 0); __builtin_amdgcn_s_setprio(0); } while (0)
; #define PG8_WAIT_V(n) asm volatile("s_waitcnt vmcnt(" #n ")" ::: "memory")
; #define PG8_WAIT_L(n) asm volatile("s_waitcnt lgkmcnt(" #n ")" ::: "memory")
; #define PG8_BAR __builtin_amdgcn_s_barrier()
; #define PG8_SCHED __builtin_amdgcn_sched_barrier(0)
; template <class Epi, class Sched>
; __device__ __forceinline__ void gemm_phase(PG8_LAS unsigned char* lds, const Gemm g, const Sched& S, const Epi& E) {
;     ...
;             PG8_STAGE(PG8_SB(0, 1), b2 + hstep, voffB);
;             PG8_WAIT_V(6); PG8_BAR; PG8_MMA(1, 1, At, B1); PG8_BAR;
;             PG8_LDB(B0, 1, 0); PG8_SCHED; PG8_LDA(At, 1, 0); PG8_STAGE(PG8_SA(0, 1), a2 + hstep, voffA);
;             PG8_WAIT_L(8); PG8_BAR; PG8_WAIT_L(0); PG8_MMA(0, 0, At, B0); PG8_BAR; PG8_SCHED;
;             PG8_LDB(B1, 1, 1); PG8_STAGE(PG8_SB(1, 0), b3, voffB);
	s_add_u32 s2, s26, 0xb0000
	s_addc_u32 s3, s27, 0
	s_add_i32 s78, s79, s10
	v_lshl_add_u64 v[130:131], s[2:3], 0, v[156:157]
	s_mov_b32 m0, s78
	s_nop 0
	global_load_lds_dwordx4 v[130:131], off
	v_lshl_add_u64 v[130:131], s[2:3], 0, v[158:159]
	s_add_i32 m0, s78, 0x2000
	s_nop 0
	global_load_lds_dwordx4 v[130:131], off
	s_waitcnt vmcnt(6)
	s_barrier
	v_mfma_f32_16x16x32_bf16 v[46:49], v[194:197], v[146:149], v[46:49]
	v_mfma_f32_16x16x32_bf16 v[42:45], v[202:205], v[146:149], v[42:45]
	v_mfma_f32_16x16x32_bf16 v[30:33], v[194:197], v[170:173], v[30:33]
	v_mfma_f32_16x16x32_bf16 v[26:29], v[202:205], v[170:173], v[26:29]
	v_mfma_f32_16x16x32_bf16 v[14:17], v[194:197], v[178:181], v[14:17]
	v_mfma_f32_16x16x32_bf16 v[10:13], v[202:205], v[178:181], v[10:13]
	v_mfma_f32_16x16x32_bf16 v[6:9], v[194:197], v[186:189], v[6:9]
	v_mfma_f32_16x16x32_bf16 v[2:5], v[202:205], v[186:189], v[2:5]
	v_mfma_f32_16x16x32_bf16 v[46:49], v[198:201], v[150:153], v[46:49]
	v_mfma_f32_16x16x32_bf16 v[42:45], v[206:209], v[150:153], v[42:45]
	v_mfma_f32_16x16x32_bf16 v[30:33], v[198:201], v[174:177], v[30:33]
	v_mfma_f32_16x16x32_bf16 v[26:29], v[206:209], v[174:177], v[26:29]
	v_mfma_f32_16x16x32_bf16 v[14:17], v[198:201], v[182:185], v[14:17]
	v_mfma_f32_16x16x32_bf16 v[10:13], v[206:209], v[182:185], v[10:13]
	v_mfma_f32_16x16x32_bf16 v[6:9], v[198:201], v[190:193], v[6:9]
	v_mfma_f32_16x16x32_bf16 v[2:5], v[206:209], v[190:193], v[2:5]
	s_add_i32 s78, 0, 0x18000
	s_barrier
	v_add_u32 v130, s53, v1
	s_nop 0
	v_add_u32_e32 v142, s78, v130
	ds_read_b128 v[130:133], v142
	ds_read_b128 v[134:137], v142 offset:1024
	ds_read_b128 v[138:141], v142 offset:2048
	ds_read_b128 v[142:145], v142 offset:3072
	s_add_u32 s2, s46, 0xb0000
	s_addc_u32 s3, s47, 0
	s_mov_b32 m0, s48
	v_add_u32 v146, s52, v1
	v_lshl_add_u64 v[194:195], s[2:3], 0, v[156:157]
	v_add_u32_e32 v169, 0, v146
	ds_read_b128 v[146:149], v169 offset:32768
	ds_read_b128 v[150:153], v169 offset:33792
	ds_read_b128 v[170:173], v169 offset:34816
	ds_read_b128 v[174:177], v169 offset:35840
	ds_read_b128 v[178:181], v169 offset:36864
	ds_read_b128 v[182:185], v169 offset:37888
	ds_read_b128 v[186:189], v169 offset:38912
	ds_read_b128 v[190:193], v169 offset:39936
	global_load_lds_dwordx4 v[194:195], off
	v_lshl_add_u64 v[194:195], s[2:3], 0, v[158:159]
	s_mov_b32 m0, s49
	s_nop 0
	global_load_lds_dwordx4 v[194:195], off
	s_waitcnt lgkmcnt(8)
	s_barrier
	s_waitcnt lgkmcnt(0)
	s_waitcnt lgkmcnt(0)
	v_mfma_f32_16x16x32_bf16 v[126:129], v[130:133], v[146:149], v[126:129]
	v_mfma_f32_16x16x32_bf16 v[122:125], v[138:141], v[146:149], v[122:125]
	v_mfma_f32_16x16x32_bf16 v[118:121], v[130:133], v[170:173], v[118:121]
	v_mfma_f32_16x16x32_bf16 v[114:117], v[138:141], v[170:173], v[114:117]
	v_mfma_f32_16x16x32_bf16 v[106:109], v[130:133], v[178:181], v[106:109]
	v_mfma_f32_16x16x32_bf16 v[98:101], v[138:141], v[178:181], v[98:101]
	v_mfma_f32_16x16x32_bf16 v[90:93], v[130:133], v[186:189], v[90:93]
	v_mfma_f32_16x16x32_bf16 v[82:85], v[138:141], v[186:189], v[82:85]
	v_mfma_f32_16x16x32_bf16 v[126:129], v[134:137], v[150:153], v[126:129]
	v_mfma_f32_16x16x32_bf16 v[122:125], v[142:145], v[150:153], v[122:125]
	v_mfma_f32_16x16x32_bf16 v[118:121], v[134:137], v[174:177], v[118:121]
	v_mfma_f32_16x16x32_bf16 v[114:117], v[142:145], v[174:177], v[114:117]
	v_mfma_f32_16x16x32_bf16 v[106:109], v[134:137], v[182:185], v[106:109]
	v_mfma_f32_16x16x32_bf16 v[98:101], v[142:145], v[182:185], v[98:101]
	v_mfma_f32_16x16x32_bf16 v[90:93], v[134:137], v[190:193], v[90:93]
	v_mfma_f32_16x16x32_bf16 v[82:85], v[142:145], v[190:193], v[82:85]
	s_barrier
	v_add_u32 v169, s53, v1
	s_add_i32 s46, 0, 0x1c000
	s_add_i32 s2, s78, s10
	v_add_u32_e32 v169, s46, v169
	v_lshl_add_u64 v[212:213], v[212:213], 0, s[30:31]
	s_mov_b32 m0, s2
	ds_read_b128 v[194:197], v169
	ds_read_b128 v[198:201], v169 offset:1024
	ds_read_b128 v[202:205], v169 offset:2048
	ds_read_b128 v[206:209], v169 offset:3072
	global_load_lds_dwordx4 v[212:213], off
	v_lshl_add_u64 v[212:213], v[214:215], 0, s[30:31]
	s_add_i32 m0, s2, 0x2000
	s_nop 0
	global_load_lds_dwordx4 v[212:213], off
	s_barrier
; #define PG8_STAGE(bufoff, gbase, voff) do { _Pragma("unroll") for (int _i = 0; _i < 2; ++_i) \
;         __builtin_amdgcn_global_load_lds((const unsigned*)((const char*)(gbase) + (voff)[_i]), (PG8_LAS unsigned*)(lds + (bufoff) + ldsw + _i * 8192), 16, 0, 0); } while (0)
; #define PG8_LDA(dst, b, h) do { int aoff; asm volatile("v_add_u32 %0, %1, %2" : "=v"(aoff) : "s"(ua), "v"(foff)); _Pragma("unroll") for (int m = 0; m < 4; ++m) _Pragma("unroll") for (int k = 0; k < 2; ++k) dst[m][k] = *(const PG8_LAS bf16x8*)(lds + PG8_SA(b, h) + aoff + m * 2048 + k * 1024); } while (0)
; #define PG8_WAIT_V(n) asm volatile("s_waitcnt vmcnt(" #n ")" ::: "memory")
; #define PG8_WAIT_L(n) asm volatile("s_waitcnt lgkmcnt(" #n ")" ::: "memory")
; #define PG8_BAR __builtin_amdgcn_s_barrier()
; #define PG8_SCHED __builtin_amdgcn_sched_barrier(0)
;     __device__ __forceinline__ void operator()(const f32x4 (&acc)[2][2][4][2], const Unit& u, int wr, int wc, int fr, int fq) const {
;         if (u.kh >= 0) {
;             float* pb = part + ((size_t)u.kh * 4096 + (size_t)(u.pm - 128) * BM + wr * 64 + fr) * 1024 + u.pn * BM + wc * 32 + 4 * fq;
; #pragma unroll
;             for (int ai = 0; ai < 2; ++ai)
; #pragma unroll
;                 for (int m = 0; m < 4; ++m)
; #pragma unroll
;                     for (int bj = 0; bj < 2; ++bj)
; #pragma unroll
;                         for (int n = 0; n < 2; ++n) *(f32x4*)(pb + (size_t)(ai * HALF + m * 16) * 1024 + bj * HALF + n * 16) = acc[ai][bj][m][n];
;             return;
;         }
;         const bool isctx = u.pm >= 128;
;         const float* inb = isctx ? in_ctx : in_lat; float* outb = isctx ? out_ctx : out_lat;
;         const int pml = isctx ? u.pm - 128 : u.pm;
;         const float* gp = gate + (size_t)(isctx ? 16 : (u.pm >> 3)) * 6144;
; template <class Epi, class Sched>
; __device__ __forceinline__ void gemm_phase(PG8_LAS unsigned char* lds, const Gemm g, const Sched& S, const Epi& E) {
;     ...
;             PG8_BAR; PG8_WAIT_L(0); PG8_MMA(0, 1, At, B1); PG8_BAR;
;             PG8_LDA(At, 1, 1); PG8_STAGE(PG8_SA(1, 0), a3, voffA);
;             PG8_BAR; PG8_WAIT_L(0); PG8_MMA(1, 0, At, B0); PG8_BAR; PG8_SCHED;
;             PG8_STAGE(PG8_SB(1, 1), b3 + hstep, voffB);
;             PG8_WAIT_V(6); PG8_BAR; PG8_MMA(1, 1, At, B1); PG8_BAR;
;         }
	s_waitcnt lgkmcnt(0)
	s_waitcnt lgkmcnt(0)
	v_mfma_f32_16x16x32_bf16 v[110:113], v[194:197], v[146:149], v[110:113]
	v_mfma_f32_16x16x32_bf16 v[102:105], v[202:205], v[146:149], v[102:105]
	v_mfma_f32_16x16x32_bf16 v[94:97], v[194:197], v[170:173], v[94:97]
	v_mfma_f32_16x16x32_bf16 v[86:89], v[202:205], v[170:173], v[86:89]
	v_mfma_f32_16x16x32_bf16 v[78:81], v[194:197], v[178:181], v[78:81]
	v_mfma_f32_16x16x32_bf16 v[74:77], v[202:205], v[178:181], v[74:77]
	v_mfma_f32_16x16x32_bf16 v[70:73], v[194:197], v[186:189], v[70:73]
	v_mfma_f32_16x16x32_bf16 v[66:69], v[202:205], v[186:189], v[66:69]
	v_mfma_f32_16x16x32_bf16 v[110:113], v[198:201], v[150:153], v[110:113]
	v_mfma_f32_16x16x32_bf16 v[102:105], v[206:209], v[150:153], v[102:105]
	v_mfma_f32_16x16x32_bf16 v[94:97], v[198:201], v[174:177], v[94:97]
	v_mfma_f32_16x16x32_bf16 v[86:89], v[206:209], v[174:177], v[86:89]
	v_mfma_f32_16x16x32_bf16 v[78:81], v[198:201], v[182:185], v[78:81]
	v_mfma_f32_16x16x32_bf16 v[74:77], v[206:209], v[182:185], v[74:77]
	v_mfma_f32_16x16x32_bf16 v[70:73], v[198:201], v[190:193], v[70:73]
	v_mfma_f32_16x16x32_bf16 v[66:69], v[206:209], v[190:193], v[66:69]
	s_mov_b32 m0, s60
	s_barrier
	v_add_u32 v146, s52, v1
	v_lshl_add_u64 v[212:213], v[218:219], 0, s[30:31]
	v_add_u32_e32 v169, 0, v146
	ds_read_b128 v[146:149], v169 offset:49152
	ds_read_b128 v[150:153], v169 offset:50176
	ds_read_b128 v[170:173], v169 offset:51200
	ds_read_b128 v[174:177], v169 offset:52224
	ds_read_b128 v[178:181], v169 offset:53248
	ds_read_b128 v[182:185], v169 offset:54272
	ds_read_b128 v[186:189], v169 offset:55296
	ds_read_b128 v[190:193], v169 offset:56320
	global_load_lds_dwordx4 v[212:213], off
	v_lshl_add_u64 v[212:213], v[220:221], 0, s[30:31]
	s_mov_b32 m0, s61
	s_nop 0
	global_load_lds_dwordx4 v[212:213], off
	s_barrier
	s_waitcnt lgkmcnt(0)
	s_waitcnt lgkmcnt(0)
	v_mfma_f32_16x16x32_bf16 v[62:65], v[130:133], v[146:149], v[62:65]
	v_mfma_f32_16x16x32_bf16 v[58:61], v[138:141], v[146:149], v[58:61]
	v_mfma_f32_16x16x32_bf16 v[54:57], v[130:133], v[170:173], v[54:57]
	v_mfma_f32_16x16x32_bf16 v[50:53], v[138:141], v[170:173], v[50:53]
	v_mfma_f32_16x16x32_bf16 v[38:41], v[130:133], v[178:181], v[38:41]
	v_mfma_f32_16x16x32_bf16 v[34:37], v[138:141], v[178:181], v[34:37]
	v_mfma_f32_16x16x32_bf16 v[22:25], v[130:133], v[186:189], v[22:25]
	v_mfma_f32_16x16x32_bf16 v[18:21], v[138:141], v[186:189], v[18:21]
	v_mfma_f32_16x16x32_bf16 v[62:65], v[134:137], v[150:153], v[62:65]
	v_mfma_f32_16x16x32_bf16 v[58:61], v[142:145], v[150:153], v[58:61]
	v_mfma_f32_16x16x32_bf16 v[54:57], v[134:137], v[174:177], v[54:57]
	v_mfma_f32_16x16x32_bf16 v[50:53], v[142:145], v[174:177], v[50:53]
	v_mfma_f32_16x16x32_bf16 v[38:41], v[134:137], v[182:185], v[38:41]
	v_mfma_f32_16x16x32_bf16 v[34:37], v[142:145], v[182:185], v[34:37]
	v_mfma_f32_16x16x32_bf16 v[22:25], v[134:137], v[190:193], v[22:25]
	v_mfma_f32_16x16x32_bf16 v[18:21], v[142:145], v[190:193], v[18:21]
	s_barrier
	s_add_u32 s2, s26, 0xb0080
	s_addc_u32 s3, s27, 0
	s_add_i32 s26, s46, s10
	v_lshl_add_u64 v[130:131], s[2:3], 0, v[156:157]
	s_mov_b32 m0, s26
	s_nop 0
	global_load_lds_dwordx4 v[130:131], off
	v_lshl_add_u64 v[130:131], s[2:3], 0, v[158:159]
	s_add_i32 m0, s26, 0x2000
	s_nop 0
	global_load_lds_dwordx4 v[130:131], off
	s_waitcnt vmcnt(6)
	s_barrier
	v_mfma_f32_16x16x32_bf16 v[46:49], v[194:197], v[146:149], v[46:49]
	v_mfma_f32_16x16x32_bf16 v[42:45], v[202:205], v[146:149], v[42:45]
	v_mfma_f32_16x16x32_bf16 v[30:33], v[194:197], v[170:173], v[30:33]
	v_mfma_f32_16x16x32_bf16 v[26:29], v[202:205], v[170:173], v[26:29]
	v_mfma_f32_16x16x32_bf16 v[14:17], v[194:197], v[178:181], v[14:17]
	v_mfma_f32_16x16x32_bf16 v[10:13], v[202:205], v[178:181], v[10:13]
	v_mfma_f32_16x16x32_bf16 v[6:9], v[194:197], v[186:189], v[6:9]
	v_mfma_f32_16x16x32_bf16 v[2:5], v[202:205], v[186:189], v[2:5]
	v_mfma_f32_16x16x32_bf16 v[46:49], v[198:201], v[150:153], v[46:49]
	v_mfma_f32_16x16x32_bf16 v[42:45], v[206:209], v[150:153], v[42:45]
	v_mfma_f32_16x16x32_bf16 v[30:33], v[198:201], v[174:177], v[30:33]
	v_mfma_f32_16x16x32_bf16 v[26:29], v[206:209], v[174:177], v[26:29]
	v_mfma_f32_16x16x32_bf16 v[14:17], v[198:201], v[182:185], v[14:17]
	v_mfma_f32_16x16x32_bf16 v[10:13], v[206:209], v[182:185], v[10:13]
	v_mfma_f32_16x16x32_bf16 v[6:9], v[198:201], v[190:193], v[6:9]
	v_mfma_f32_16x16x32_bf16 v[2:5], v[206:209], v[190:193], v[2:5]
	s_add_u32 s21, s21, 0x100
	s_addc_u32 s25, s25, 0
	s_cmp_ge_u32 s54, s19
	s_mov_b64 s[2:3], s[16:17]
	s_mov_b32 s26, s54
	s_barrier
	s_cbranch_scc0 .LBB0_1195
	s_cmp_lt_i32 s20, 0
	s_mov_b64 s[2:3], -1
	s_cbranch_scc0 .LBB0_1200
	s_cmpk_gt_i32 s18, 0x7f
	s_cselect_b64 s[16:17], -1, 0
	s_mov_b64 s[26:27], 0x18000
	s_and_b64 vcc, exec, s[16:17]
	s_cbranch_vccnz .LBB0_1199
	s_ashr_i32 s2, s18, 3
	s_mul_hi_i32 s27, s2, 0x1800
	s_mul_i32 s26, s2, 0x1800
